# P0 weight transposes: issue the whole 64x32 tile (32 loads; 48 for the LayerNorm-folding variant) before converting instead of waiting per batch/element; sample-item scoring waves on different SIMDs;
# speedup vs baseline: 1.0647x; 1.0327x over previous
.LBB0_26:
	v_lshl_add_u64 v[48:49], v[46:47], 0, s[14:15]
	v_lshl_add_u64 v[50:51], v[44:45], 0, s[14:15]
	v_lshl_add_u64 v[52:53], v[42:43], 0, s[14:15]
	v_lshl_add_u64 v[54:55], v[40:41], 0, s[14:15]
	v_lshl_add_u64 v[56:57], v[38:39], 0, s[14:15]
	v_lshl_add_u64 v[72:73], v[36:37], 0, s[14:15]
	v_lshl_add_u64 v[74:75], v[34:35], 0, s[14:15]
	v_lshl_add_u64 v[76:77], v[32:33], 0, s[14:15]
	global_load_dword v100, v[48:49], off nt
	global_load_dword v101, v[50:51], off nt
	global_load_dword v102, v[52:53], off nt
	global_load_dword v103, v[54:55], off nt
	global_load_dword v104, v[56:57], off nt
	global_load_dword v105, v[72:73], off nt
	global_load_dword v106, v[74:75], off nt
	global_load_dword v107, v[76:77], off nt
	s_add_u32 s14, s14, 0x10000
	s_addc_u32 s15, s15, 0
	v_lshl_add_u64 v[48:49], v[46:47], 0, s[14:15]
	v_lshl_add_u64 v[50:51], v[44:45], 0, s[14:15]
	v_lshl_add_u64 v[52:53], v[42:43], 0, s[14:15]
	v_lshl_add_u64 v[54:55], v[40:41], 0, s[14:15]
	v_lshl_add_u64 v[56:57], v[38:39], 0, s[14:15]
	v_lshl_add_u64 v[72:73], v[36:37], 0, s[14:15]
	v_lshl_add_u64 v[74:75], v[34:35], 0, s[14:15]
	v_lshl_add_u64 v[76:77], v[32:33], 0, s[14:15]
	global_load_dword v108, v[48:49], off nt
	global_load_dword v109, v[50:51], off nt
	global_load_dword v110, v[52:53], off nt
	global_load_dword v111, v[54:55], off nt
	global_load_dword v112, v[56:57], off nt
	global_load_dword v113, v[72:73], off nt
	global_load_dword v114, v[74:75], off nt
	global_load_dword v115, v[76:77], off nt
	s_add_u32 s14, s14, 0x10000
	s_addc_u32 s15, s15, 0
	v_lshl_add_u64 v[48:49], v[46:47], 0, s[14:15]
	v_lshl_add_u64 v[50:51], v[44:45], 0, s[14:15]
	v_lshl_add_u64 v[52:53], v[42:43], 0, s[14:15]
	v_lshl_add_u64 v[54:55], v[40:41], 0, s[14:15]
	v_lshl_add_u64 v[56:57], v[38:39], 0, s[14:15]
	v_lshl_add_u64 v[72:73], v[36:37], 0, s[14:15]
	v_lshl_add_u64 v[74:75], v[34:35], 0, s[14:15]
	v_lshl_add_u64 v[76:77], v[32:33], 0, s[14:15]
	global_load_dword v116, v[48:49], off nt
	global_load_dword v117, v[50:51], off nt
	global_load_dword v118, v[52:53], off nt
	global_load_dword v119, v[54:55], off nt
	global_load_dword v120, v[56:57], off nt
	global_load_dword v121, v[72:73], off nt
	global_load_dword v122, v[74:75], off nt
	global_load_dword v123, v[76:77], off nt
	s_add_u32 s14, s14, 0x10000
	s_addc_u32 s15, s15, 0
	v_lshl_add_u64 v[48:49], v[46:47], 0, s[14:15]
	v_lshl_add_u64 v[50:51], v[44:45], 0, s[14:15]
	v_lshl_add_u64 v[52:53], v[42:43], 0, s[14:15]
	v_lshl_add_u64 v[54:55], v[40:41], 0, s[14:15]
	v_lshl_add_u64 v[56:57], v[38:39], 0, s[14:15]
	v_lshl_add_u64 v[72:73], v[36:37], 0, s[14:15]
	v_lshl_add_u64 v[74:75], v[34:35], 0, s[14:15]
	v_lshl_add_u64 v[76:77], v[32:33], 0, s[14:15]
	global_load_dword v124, v[48:49], off nt
	global_load_dword v125, v[50:51], off nt
	global_load_dword v126, v[52:53], off nt
	global_load_dword v127, v[54:55], off nt
	global_load_dword v128, v[56:57], off nt
	global_load_dword v129, v[72:73], off nt
	global_load_dword v130, v[74:75], off nt
	global_load_dword v131, v[76:77], off nt
	s_add_u32 s14, s14, 0x10000
	s_addc_u32 s15, s15, 0
	v_add_u32_e32 v56, 0x400, v2
	s_waitcnt vmcnt(30)
	ds_write2_b32 v2, v100, v101 offset1:66
	s_waitcnt vmcnt(28)
	ds_write2_b32 v2, v102, v103 offset0:132 offset1:198
	s_waitcnt vmcnt(26)
	ds_write2_b32 v56, v104, v105 offset0:8 offset1:74
	s_waitcnt vmcnt(24)
	ds_write2_b32 v56, v106, v107 offset0:140 offset1:206
	v_add_u32_e32 v2, 0x840, v2
	v_add_u32_e32 v56, 0x400, v2
	s_waitcnt vmcnt(22)
	ds_write2_b32 v2, v108, v109 offset1:66
	s_waitcnt vmcnt(20)
	ds_write2_b32 v2, v110, v111 offset0:132 offset1:198
	s_waitcnt vmcnt(18)
	ds_write2_b32 v56, v112, v113 offset0:8 offset1:74
	s_waitcnt vmcnt(16)
	ds_write2_b32 v56, v114, v115 offset0:140 offset1:206
	v_add_u32_e32 v2, 0x840, v2
	v_add_u32_e32 v56, 0x400, v2
	s_waitcnt vmcnt(14)
	ds_write2_b32 v2, v116, v117 offset1:66
	s_waitcnt vmcnt(12)
	ds_write2_b32 v2, v118, v119 offset0:132 offset1:198
	s_waitcnt vmcnt(10)
	ds_write2_b32 v56, v120, v121 offset0:8 offset1:74
	s_waitcnt vmcnt(8)
	ds_write2_b32 v56, v122, v123 offset0:140 offset1:206
	v_add_u32_e32 v2, 0x840, v2
	v_add_u32_e32 v56, 0x400, v2
	s_waitcnt vmcnt(6)
	ds_write2_b32 v2, v124, v125 offset1:66
	s_waitcnt vmcnt(4)
	ds_write2_b32 v2, v126, v127 offset0:132 offset1:198
	s_waitcnt vmcnt(2)
	ds_write2_b32 v56, v128, v129 offset0:8 offset1:74
	s_waitcnt vmcnt(0)
	ds_write2_b32 v56, v130, v131 offset0:140 offset1:206
	v_add_u32_e32 v2, 0x840, v2
	s_add_i32 s14, s46, 0xfffff180
	s_lshl_b32 s35, s14, 1
	s_waitcnt lgkmcnt(0)
	s_and_b32 s35, s35, 0xfffffc00
	ds_read2_b32 v[32:33], v58 offset1:33
	s_lshl_b32 s14, s14, 2
	s_or_b32 s35, s35, s34
	s_waitcnt lgkmcnt(0)
	v_cvt_pk_bf16_f32 v32, v32, v33
	ds_read2_b32 v[34:35], v58 offset0:66 offset1:99
	s_mov_b32 s15, s1
	s_and_b32 s14, s14, 0x780
	v_or_b32_e32 v2, s35, v1
	s_waitcnt lgkmcnt(0)
	v_cvt_pk_bf16_f32 v33, v34, v35
	ds_read2_b32 v[34:35], v58 offset0:132 offset1:165
	v_lshl_add_u64 v[38:39], v[4:5], 0, s[14:15]
	v_lshlrev_b64 v[40:41], 11, v[2:3]
	s_waitcnt lgkmcnt(0)
	v_cvt_pk_bf16_f32 v34, v34, v35
	ds_read2_b32 v[36:37], v58 offset0:198 offset1:231
	s_waitcnt lgkmcnt(0)
	v_cvt_pk_bf16_f32 v35, v36, v37
	v_lshl_add_u64 v[40:41], v[38:39], 0, v[40:41]
	ds_read2_b32 v[36:37], v58 offset0:8 offset1:41
	global_store_dwordx4 v[40:41], v[32:35], off
	v_or_b32_e32 v2, s35, v59
	v_lshlrev_b64 v[40:41], 11, v[2:3]
	s_waitcnt lgkmcnt(0)
	v_cvt_pk_bf16_f32 v32, v36, v37
	ds_read2_b32 v[34:35], v58 offset0:74 offset1:107
	s_waitcnt lgkmcnt(0)
	v_cvt_pk_bf16_f32 v33, v34, v35
	ds_read2_b32 v[34:35], v58 offset0:140 offset1:173
	s_waitcnt lgkmcnt(0)
	v_cvt_pk_bf16_f32 v34, v34, v35
	ds_read2_b32 v[36:37], v58 offset0:206 offset1:239
	s_waitcnt lgkmcnt(0)
	v_cvt_pk_bf16_f32 v35, v36, v37
	v_lshl_add_u64 v[40:41], v[38:39], 0, v[40:41]
	ds_read2_b32 v[36:37], v58 offset0:16 offset1:49
	global_store_dwordx4 v[40:41], v[32:35], off
	v_or_b32_e32 v2, s35, v60
	v_lshlrev_b64 v[40:41], 11, v[2:3]
	s_waitcnt lgkmcnt(0)
	v_cvt_pk_bf16_f32 v32, v36, v37
	ds_read2_b32 v[34:35], v58 offset0:82 offset1:115
	s_waitcnt lgkmcnt(0)
	v_cvt_pk_bf16_f32 v33, v34, v35
	ds_read2_b32 v[34:35], v58 offset0:148 offset1:181
	s_waitcnt lgkmcnt(0)
	v_cvt_pk_bf16_f32 v34, v34, v35
	ds_read2_b32 v[36:37], v58 offset0:214 offset1:247
	s_waitcnt lgkmcnt(0)
	v_cvt_pk_bf16_f32 v35, v36, v37
	v_lshl_add_u64 v[40:41], v[38:39], 0, v[40:41]
	ds_read2_b32 v[36:37], v58 offset0:24 offset1:57
	global_store_dwordx4 v[40:41], v[32:35], off
	v_or_b32_e32 v2, s35, v61
	v_lshlrev_b64 v[40:41], 11, v[2:3]
	s_waitcnt lgkmcnt(0)
	v_cvt_pk_bf16_f32 v32, v36, v37
	ds_read2_b32 v[34:35], v58 offset0:90 offset1:123
	s_waitcnt lgkmcnt(0)
	v_cvt_pk_bf16_f32 v33, v34, v35
	ds_read2_b32 v[34:35], v58 offset0:156 offset1:189
	s_waitcnt lgkmcnt(0)
	v_cvt_pk_bf16_f32 v34, v34, v35
	ds_read2_b32 v[36:37], v58 offset0:222 offset1:255
	s_waitcnt lgkmcnt(0)
	v_cvt_pk_bf16_f32 v35, v36, v37
	v_lshl_add_u64 v[36:37], v[38:39], 0, v[40:41]
	global_store_dwordx4 v[36:37], v[32:35], off
	s_waitcnt lgkmcnt(0)
	s_mov_b64 s[14:15], 0

.LBB0_30:
	v_lshl_add_u64 v[48:49], v[46:47], 0, s[14:15]
	v_lshl_add_u64 v[50:51], v[44:45], 0, s[14:15]
	v_lshl_add_u64 v[52:53], v[42:43], 0, s[14:15]
	v_lshl_add_u64 v[54:55], v[40:41], 0, s[14:15]
	v_lshl_add_u64 v[56:57], v[38:39], 0, s[14:15]
	v_lshl_add_u64 v[72:73], v[36:37], 0, s[14:15]
	v_lshl_add_u64 v[74:75], v[34:35], 0, s[14:15]
	v_lshl_add_u64 v[76:77], v[32:33], 0, s[14:15]
	global_load_dword v100, v[48:49], off nt
	global_load_dword v101, v[50:51], off nt
	global_load_dword v102, v[52:53], off nt
	global_load_dword v103, v[54:55], off nt
	global_load_dword v104, v[56:57], off nt
	global_load_dword v105, v[72:73], off nt
	global_load_dword v106, v[74:75], off nt
	global_load_dword v107, v[76:77], off nt
	s_add_u32 s14, s14, 0x10000
	s_addc_u32 s15, s15, 0
	v_lshl_add_u64 v[48:49], v[46:47], 0, s[14:15]
	v_lshl_add_u64 v[50:51], v[44:45], 0, s[14:15]
	v_lshl_add_u64 v[52:53], v[42:43], 0, s[14:15]
	v_lshl_add_u64 v[54:55], v[40:41], 0, s[14:15]
	v_lshl_add_u64 v[56:57], v[38:39], 0, s[14:15]
	v_lshl_add_u64 v[72:73], v[36:37], 0, s[14:15]
	v_lshl_add_u64 v[74:75], v[34:35], 0, s[14:15]
	v_lshl_add_u64 v[76:77], v[32:33], 0, s[14:15]
	global_load_dword v108, v[48:49], off nt
	global_load_dword v109, v[50:51], off nt
	global_load_dword v110, v[52:53], off nt
	global_load_dword v111, v[54:55], off nt
	global_load_dword v112, v[56:57], off nt
	global_load_dword v113, v[72:73], off nt
	global_load_dword v114, v[74:75], off nt
	global_load_dword v115, v[76:77], off nt
	s_add_u32 s14, s14, 0x10000
	s_addc_u32 s15, s15, 0
	v_lshl_add_u64 v[48:49], v[46:47], 0, s[14:15]
	v_lshl_add_u64 v[50:51], v[44:45], 0, s[14:15]
	v_lshl_add_u64 v[52:53], v[42:43], 0, s[14:15]
	v_lshl_add_u64 v[54:55], v[40:41], 0, s[14:15]
	v_lshl_add_u64 v[56:57], v[38:39], 0, s[14:15]
	v_lshl_add_u64 v[72:73], v[36:37], 0, s[14:15]
	v_lshl_add_u64 v[74:75], v[34:35], 0, s[14:15]
	v_lshl_add_u64 v[76:77], v[32:33], 0, s[14:15]
	global_load_dword v116, v[48:49], off nt
	global_load_dword v117, v[50:51], off nt
	global_load_dword v118, v[52:53], off nt
	global_load_dword v119, v[54:55], off nt
	global_load_dword v120, v[56:57], off nt
	global_load_dword v121, v[72:73], off nt
	global_load_dword v122, v[74:75], off nt
	global_load_dword v123, v[76:77], off nt
	s_add_u32 s14, s14, 0x10000
	s_addc_u32 s15, s15, 0
	v_lshl_add_u64 v[48:49], v[46:47], 0, s[14:15]
	v_lshl_add_u64 v[50:51], v[44:45], 0, s[14:15]
	v_lshl_add_u64 v[52:53], v[42:43], 0, s[14:15]
	v_lshl_add_u64 v[54:55], v[40:41], 0, s[14:15]
	v_lshl_add_u64 v[56:57], v[38:39], 0, s[14:15]
	v_lshl_add_u64 v[72:73], v[36:37], 0, s[14:15]
	v_lshl_add_u64 v[74:75], v[34:35], 0, s[14:15]
	v_lshl_add_u64 v[76:77], v[32:33], 0, s[14:15]
	global_load_dword v124, v[48:49], off nt
	global_load_dword v125, v[50:51], off nt
	global_load_dword v126, v[52:53], off nt
	global_load_dword v127, v[54:55], off nt
	global_load_dword v128, v[56:57], off nt
	global_load_dword v129, v[72:73], off nt
	global_load_dword v130, v[74:75], off nt
	global_load_dword v131, v[76:77], off nt
	s_add_u32 s14, s14, 0x10000
	s_addc_u32 s15, s15, 0
	v_add_u32_e32 v56, 0x400, v2
	s_waitcnt vmcnt(30)
	ds_write2_b32 v2, v100, v101 offset1:66
	s_waitcnt vmcnt(28)
	ds_write2_b32 v2, v102, v103 offset0:132 offset1:198
	s_waitcnt vmcnt(26)
	ds_write2_b32 v56, v104, v105 offset0:8 offset1:74
	s_waitcnt vmcnt(24)
	ds_write2_b32 v56, v106, v107 offset0:140 offset1:206
	v_add_u32_e32 v2, 0x840, v2
	v_add_u32_e32 v56, 0x400, v2
	s_waitcnt vmcnt(22)
	ds_write2_b32 v2, v108, v109 offset1:66
	s_waitcnt vmcnt(20)
	ds_write2_b32 v2, v110, v111 offset0:132 offset1:198
	s_waitcnt vmcnt(18)
	ds_write2_b32 v56, v112, v113 offset0:8 offset1:74
	s_waitcnt vmcnt(16)
	ds_write2_b32 v56, v114, v115 offset0:140 offset1:206
	v_add_u32_e32 v2, 0x840, v2
	v_add_u32_e32 v56, 0x400, v2
	s_waitcnt vmcnt(14)
	ds_write2_b32 v2, v116, v117 offset1:66
	s_waitcnt vmcnt(12)
	ds_write2_b32 v2, v118, v119 offset0:132 offset1:198
	s_waitcnt vmcnt(10)
	ds_write2_b32 v56, v120, v121 offset0:8 offset1:74
	s_waitcnt vmcnt(8)
	ds_write2_b32 v56, v122, v123 offset0:140 offset1:206
	v_add_u32_e32 v2, 0x840, v2
	v_add_u32_e32 v56, 0x400, v2
	s_waitcnt vmcnt(6)
	ds_write2_b32 v2, v124, v125 offset1:66
	s_waitcnt vmcnt(4)
	ds_write2_b32 v2, v126, v127 offset0:132 offset1:198
	s_waitcnt vmcnt(2)
	ds_write2_b32 v56, v128, v129 offset0:8 offset1:74
	s_waitcnt vmcnt(0)
	ds_write2_b32 v56, v130, v131 offset0:140 offset1:206
	v_add_u32_e32 v2, 0x840, v2
	s_add_i32 s0, s46, 0xfffff580
	s_lshl_b32 s14, s0, 1
	s_waitcnt lgkmcnt(0)
	s_and_b32 s14, s14, 0xfffffc00
	ds_read2_b32 v[32:33], v58 offset1:33
	s_lshl_b32 s0, s0, 2
	s_or_b32 s14, s14, s34
	s_waitcnt lgkmcnt(0)
	v_cvt_pk_bf16_f32 v32, v32, v33
	ds_read2_b32 v[34:35], v58 offset0:66 offset1:99
	s_and_b32 s0, s0, 0x780
	v_or_b32_e32 v2, s14, v1
	s_waitcnt lgkmcnt(0)
	v_cvt_pk_bf16_f32 v33, v34, v35
	ds_read2_b32 v[34:35], v58 offset0:132 offset1:165
	v_lshl_add_u64 v[38:39], v[6:7], 0, s[0:1]
	v_lshlrev_b64 v[40:41], 11, v[2:3]
	s_waitcnt lgkmcnt(0)
	v_cvt_pk_bf16_f32 v34, v34, v35
	ds_read2_b32 v[36:37], v58 offset0:198 offset1:231
	s_waitcnt lgkmcnt(0)
	v_cvt_pk_bf16_f32 v35, v36, v37
	v_lshl_add_u64 v[40:41], v[38:39], 0, v[40:41]
	ds_read2_b32 v[36:37], v58 offset0:8 offset1:41
	global_store_dwordx4 v[40:41], v[32:35], off
	v_or_b32_e32 v2, s14, v59
	v_lshlrev_b64 v[40:41], 11, v[2:3]
	s_waitcnt lgkmcnt(0)
	v_cvt_pk_bf16_f32 v32, v36, v37
	ds_read2_b32 v[34:35], v58 offset0:74 offset1:107
	s_waitcnt lgkmcnt(0)
	v_cvt_pk_bf16_f32 v33, v34, v35
	ds_read2_b32 v[34:35], v58 offset0:140 offset1:173
	s_waitcnt lgkmcnt(0)
	v_cvt_pk_bf16_f32 v34, v34, v35
	ds_read2_b32 v[36:37], v58 offset0:206 offset1:239
	s_waitcnt lgkmcnt(0)
	v_cvt_pk_bf16_f32 v35, v36, v37
	v_lshl_add_u64 v[40:41], v[38:39], 0, v[40:41]
	ds_read2_b32 v[36:37], v58 offset0:16 offset1:49
	global_store_dwordx4 v[40:41], v[32:35], off
	v_or_b32_e32 v2, s14, v60
	v_lshlrev_b64 v[40:41], 11, v[2:3]
	s_waitcnt lgkmcnt(0)
	v_cvt_pk_bf16_f32 v32, v36, v37
	ds_read2_b32 v[34:35], v58 offset0:82 offset1:115
	s_waitcnt lgkmcnt(0)
	v_cvt_pk_bf16_f32 v33, v34, v35
	ds_read2_b32 v[34:35], v58 offset0:148 offset1:181
	s_waitcnt lgkmcnt(0)
	v_cvt_pk_bf16_f32 v34, v34, v35
	ds_read2_b32 v[36:37], v58 offset0:214 offset1:247
	s_waitcnt lgkmcnt(0)
	v_cvt_pk_bf16_f32 v35, v36, v37
	v_lshl_add_u64 v[40:41], v[38:39], 0, v[40:41]
	ds_read2_b32 v[36:37], v58 offset0:24 offset1:57
	global_store_dwordx4 v[40:41], v[32:35], off
	v_or_b32_e32 v2, s14, v61
	v_lshlrev_b64 v[40:41], 11, v[2:3]
	s_waitcnt lgkmcnt(0)
	v_cvt_pk_bf16_f32 v32, v36, v37
	ds_read2_b32 v[34:35], v58 offset0:90 offset1:123
	s_waitcnt lgkmcnt(0)
	v_cvt_pk_bf16_f32 v33, v34, v35
	ds_read2_b32 v[34:35], v58 offset0:156 offset1:189
	s_waitcnt lgkmcnt(0)
	v_cvt_pk_bf16_f32 v34, v34, v35
	ds_read2_b32 v[36:37], v58 offset0:222 offset1:255
	s_waitcnt lgkmcnt(0)
	v_cvt_pk_bf16_f32 v35, v36, v37
	v_lshl_add_u64 v[36:37], v[38:39], 0, v[40:41]
	global_store_dwordx4 v[36:37], v[32:35], off
	s_waitcnt lgkmcnt(0)

.LBB0_35:
	v_lshl_add_u64 v[72:73], v[50:51], 0, v[18:19]
	global_load_dword v100, v[72:73], off nt
	v_lshl_add_u64 v[50:51], v[50:51], 0, s[8:9]
	v_lshl_add_u64 v[72:73], v[44:45], 0, v[18:19]
	global_load_dword v101, v[72:73], off nt
	v_lshl_add_u64 v[44:45], v[44:45], 0, s[8:9]
	v_lshl_add_u64 v[72:73], v[42:43], 0, v[18:19]
	global_load_dword v102, v[72:73], off nt
	v_lshl_add_u64 v[42:43], v[42:43], 0, s[8:9]
	v_lshl_add_u64 v[72:73], v[40:41], 0, v[18:19]
	global_load_dword v103, v[72:73], off nt
	v_lshl_add_u64 v[40:41], v[40:41], 0, s[8:9]
	v_lshl_add_u64 v[72:73], v[38:39], 0, v[18:19]
	global_load_dword v104, v[72:73], off nt
	v_lshl_add_u64 v[38:39], v[38:39], 0, s[8:9]
	v_lshl_add_u64 v[72:73], v[36:37], 0, v[18:19]
	global_load_dword v105, v[72:73], off nt
	v_lshl_add_u64 v[36:37], v[36:37], 0, s[8:9]
	v_lshl_add_u64 v[72:73], v[34:35], 0, v[18:19]
	global_load_dword v106, v[72:73], off nt
	v_lshl_add_u64 v[34:35], v[34:35], 0, s[8:9]
	v_lshl_add_u64 v[72:73], v[32:33], 0, v[18:19]
	global_load_dword v107, v[72:73], off nt
	v_lshl_add_u64 v[32:33], v[32:33], 0, s[8:9]
	v_lshl_add_u64 v[74:75], v[52:53], 0, s[14:15]
	global_load_dword v116, v[74:75], off
	v_lshl_add_u64 v[74:75], v[48:49], 0, s[14:15]
	global_load_dword v117, v[74:75], off offset:8
	global_load_dword v118, v[74:75], off offset:16
	global_load_dword v119, v[74:75], off offset:24
	global_load_dword v120, v[74:75], off offset:32
	global_load_dword v121, v[74:75], off offset:40
	global_load_dword v122, v[74:75], off offset:48
	global_load_dword v123, v[74:75], off offset:56
	v_lshl_add_u64 v[76:77], v[54:55], 0, s[14:15]
	global_load_dword v132, v[76:77], off
	v_lshl_add_u64 v[76:77], v[46:47], 0, s[14:15]
	global_load_dword v133, v[76:77], off offset:8
	global_load_dword v134, v[76:77], off offset:16
	global_load_dword v135, v[76:77], off offset:24
	global_load_dword v136, v[76:77], off offset:32
	global_load_dword v137, v[76:77], off offset:40
	global_load_dword v138, v[76:77], off offset:48
	global_load_dword v139, v[76:77], off offset:56
	s_add_u32 s14, s14, 64
	s_addc_u32 s15, s15, 0
	v_lshl_add_u64 v[72:73], v[50:51], 0, v[18:19]
	global_load_dword v108, v[72:73], off nt
	v_lshl_add_u64 v[50:51], v[50:51], 0, s[8:9]
	v_lshl_add_u64 v[72:73], v[44:45], 0, v[18:19]
	global_load_dword v109, v[72:73], off nt
	v_lshl_add_u64 v[44:45], v[44:45], 0, s[8:9]
	v_lshl_add_u64 v[72:73], v[42:43], 0, v[18:19]
	global_load_dword v110, v[72:73], off nt
	v_lshl_add_u64 v[42:43], v[42:43], 0, s[8:9]
	v_lshl_add_u64 v[72:73], v[40:41], 0, v[18:19]
	global_load_dword v111, v[72:73], off nt
	v_lshl_add_u64 v[40:41], v[40:41], 0, s[8:9]
	v_lshl_add_u64 v[72:73], v[38:39], 0, v[18:19]
	global_load_dword v112, v[72:73], off nt
	v_lshl_add_u64 v[38:39], v[38:39], 0, s[8:9]
	v_lshl_add_u64 v[72:73], v[36:37], 0, v[18:19]
	global_load_dword v113, v[72:73], off nt
	v_lshl_add_u64 v[36:37], v[36:37], 0, s[8:9]
	v_lshl_add_u64 v[72:73], v[34:35], 0, v[18:19]
	global_load_dword v114, v[72:73], off nt
	v_lshl_add_u64 v[34:35], v[34:35], 0, s[8:9]
	v_lshl_add_u64 v[72:73], v[32:33], 0, v[18:19]
	global_load_dword v115, v[72:73], off nt
	v_lshl_add_u64 v[32:33], v[32:33], 0, s[8:9]
	v_lshl_add_u64 v[74:75], v[52:53], 0, s[14:15]
	global_load_dword v124, v[74:75], off
	v_lshl_add_u64 v[74:75], v[48:49], 0, s[14:15]
	global_load_dword v125, v[74:75], off offset:8
	global_load_dword v126, v[74:75], off offset:16
	global_load_dword v127, v[74:75], off offset:24
	global_load_dword v128, v[74:75], off offset:32
	global_load_dword v129, v[74:75], off offset:40
	global_load_dword v130, v[74:75], off offset:48
	global_load_dword v131, v[74:75], off offset:56
	v_lshl_add_u64 v[76:77], v[54:55], 0, s[14:15]
	global_load_dword v140, v[76:77], off
	v_lshl_add_u64 v[76:77], v[46:47], 0, s[14:15]
	global_load_dword v141, v[76:77], off offset:8
	global_load_dword v142, v[76:77], off offset:16
	global_load_dword v143, v[76:77], off offset:24
	global_load_dword v144, v[76:77], off offset:32
	global_load_dword v145, v[76:77], off offset:40
	global_load_dword v146, v[76:77], off offset:48
	global_load_dword v147, v[76:77], off offset:56
	s_add_u32 s14, s14, 64
	s_addc_u32 s15, s15, 0
	s_waitcnt vmcnt(0)
	v_mul_f32_e32 v78, v100, v116
	ds_write_b32 v2, v78
	v_cvt_pk_bf16_f32 v79, v78, v3
	v_mul_f32_e32 v72, v100, v132
	v_lshlrev_b32_e32 v73, 16, v79
	v_pk_add_f32 v[56:57], v[56:57], v[72:73]
	v_mul_f32_e32 v78, v101, v117
	ds_write_b32 v2, v78 offset:264
	v_cvt_pk_bf16_f32 v79, v78, v3
	v_mul_f32_e32 v72, v101, v133
	v_lshlrev_b32_e32 v73, 16, v79
	v_pk_add_f32 v[56:57], v[56:57], v[72:73]
	v_mul_f32_e32 v78, v102, v118
	ds_write_b32 v2, v78 offset:528
	v_cvt_pk_bf16_f32 v79, v78, v3
	v_mul_f32_e32 v72, v102, v134
	v_lshlrev_b32_e32 v73, 16, v79
	v_pk_add_f32 v[56:57], v[56:57], v[72:73]
	v_mul_f32_e32 v78, v103, v119
	ds_write_b32 v2, v78 offset:792
	v_cvt_pk_bf16_f32 v79, v78, v3
	v_mul_f32_e32 v72, v103, v135
	v_lshlrev_b32_e32 v73, 16, v79
	v_pk_add_f32 v[56:57], v[56:57], v[72:73]
	v_mul_f32_e32 v78, v104, v120
	ds_write_b32 v2, v78 offset:1056
	v_cvt_pk_bf16_f32 v79, v78, v3
	v_mul_f32_e32 v72, v104, v136
	v_lshlrev_b32_e32 v73, 16, v79
	v_pk_add_f32 v[56:57], v[56:57], v[72:73]
	v_mul_f32_e32 v78, v105, v121
	ds_write_b32 v2, v78 offset:1320
	v_cvt_pk_bf16_f32 v79, v78, v3
	v_mul_f32_e32 v72, v105, v137
	v_lshlrev_b32_e32 v73, 16, v79
	v_pk_add_f32 v[56:57], v[56:57], v[72:73]
	v_mul_f32_e32 v78, v106, v122
	ds_write_b32 v2, v78 offset:1584
	v_cvt_pk_bf16_f32 v79, v78, v3
	v_mul_f32_e32 v72, v106, v138
	v_lshlrev_b32_e32 v73, 16, v79
	v_pk_add_f32 v[56:57], v[56:57], v[72:73]
	v_mul_f32_e32 v78, v107, v123
	ds_write_b32 v2, v78 offset:1848
	v_cvt_pk_bf16_f32 v79, v78, v3
	v_mul_f32_e32 v72, v107, v139
	v_lshlrev_b32_e32 v73, 16, v79
	v_pk_add_f32 v[56:57], v[56:57], v[72:73]
	v_add_u32_e32 v2, 0x840, v2
	v_mul_f32_e32 v78, v108, v124
	ds_write_b32 v2, v78
	v_cvt_pk_bf16_f32 v79, v78, v3
	v_mul_f32_e32 v72, v108, v140
	v_lshlrev_b32_e32 v73, 16, v79
	v_pk_add_f32 v[56:57], v[56:57], v[72:73]
	v_mul_f32_e32 v78, v109, v125
	ds_write_b32 v2, v78 offset:264
	v_cvt_pk_bf16_f32 v79, v78, v3
	v_mul_f32_e32 v72, v109, v141
	v_lshlrev_b32_e32 v73, 16, v79
	v_pk_add_f32 v[56:57], v[56:57], v[72:73]
	v_mul_f32_e32 v78, v110, v126
	ds_write_b32 v2, v78 offset:528
	v_cvt_pk_bf16_f32 v79, v78, v3
	v_mul_f32_e32 v72, v110, v142
	v_lshlrev_b32_e32 v73, 16, v79
	v_pk_add_f32 v[56:57], v[56:57], v[72:73]
	v_mul_f32_e32 v78, v111, v127
	ds_write_b32 v2, v78 offset:792
	v_cvt_pk_bf16_f32 v79, v78, v3
	v_mul_f32_e32 v72, v111, v143
	v_lshlrev_b32_e32 v73, 16, v79
	v_pk_add_f32 v[56:57], v[56:57], v[72:73]
	v_mul_f32_e32 v78, v112, v128
	ds_write_b32 v2, v78 offset:1056
	v_cvt_pk_bf16_f32 v79, v78, v3
	v_mul_f32_e32 v72, v112, v144
	v_lshlrev_b32_e32 v73, 16, v79
	v_pk_add_f32 v[56:57], v[56:57], v[72:73]
	v_mul_f32_e32 v78, v113, v129
	ds_write_b32 v2, v78 offset:1320
	v_cvt_pk_bf16_f32 v79, v78, v3
	v_mul_f32_e32 v72, v113, v145
	v_lshlrev_b32_e32 v73, 16, v79
	v_pk_add_f32 v[56:57], v[56:57], v[72:73]
	v_mul_f32_e32 v78, v114, v130
	ds_write_b32 v2, v78 offset:1584
	v_cvt_pk_bf16_f32 v79, v78, v3
	v_mul_f32_e32 v72, v114, v146
	v_lshlrev_b32_e32 v73, 16, v79
	v_pk_add_f32 v[56:57], v[56:57], v[72:73]
	v_mul_f32_e32 v78, v115, v131
	ds_write_b32 v2, v78 offset:1848
	v_cvt_pk_bf16_f32 v79, v78, v3
	v_mul_f32_e32 v72, v115, v147
	v_lshlrev_b32_e32 v73, 16, v79
	v_pk_add_f32 v[56:57], v[56:57], v[72:73]
	v_add_u32_e32 v2, 0x840, v2
	v_lshl_add_u64 v[72:73], v[50:51], 0, v[18:19]
	global_load_dword v100, v[72:73], off nt
	v_lshl_add_u64 v[50:51], v[50:51], 0, s[8:9]
	v_lshl_add_u64 v[72:73], v[44:45], 0, v[18:19]
	global_load_dword v101, v[72:73], off nt
	v_lshl_add_u64 v[44:45], v[44:45], 0, s[8:9]
	v_lshl_add_u64 v[72:73], v[42:43], 0, v[18:19]
	global_load_dword v102, v[72:73], off nt
	v_lshl_add_u64 v[42:43], v[42:43], 0, s[8:9]
	v_lshl_add_u64 v[72:73], v[40:41], 0, v[18:19]
	global_load_dword v103, v[72:73], off nt
	v_lshl_add_u64 v[40:41], v[40:41], 0, s[8:9]
	v_lshl_add_u64 v[72:73], v[38:39], 0, v[18:19]
	global_load_dword v104, v[72:73], off nt
	v_lshl_add_u64 v[38:39], v[38:39], 0, s[8:9]
	v_lshl_add_u64 v[72:73], v[36:37], 0, v[18:19]
	global_load_dword v105, v[72:73], off nt
	v_lshl_add_u64 v[36:37], v[36:37], 0, s[8:9]
	v_lshl_add_u64 v[72:73], v[34:35], 0, v[18:19]
	global_load_dword v106, v[72:73], off nt
	v_lshl_add_u64 v[34:35], v[34:35], 0, s[8:9]
	v_lshl_add_u64 v[72:73], v[32:33], 0, v[18:19]
	global_load_dword v107, v[72:73], off nt
	v_lshl_add_u64 v[32:33], v[32:33], 0, s[8:9]
	v_lshl_add_u64 v[74:75], v[52:53], 0, s[14:15]
	global_load_dword v116, v[74:75], off
	v_lshl_add_u64 v[74:75], v[48:49], 0, s[14:15]
	global_load_dword v117, v[74:75], off offset:8
	global_load_dword v118, v[74:75], off offset:16
	global_load_dword v119, v[74:75], off offset:24
	global_load_dword v120, v[74:75], off offset:32
	global_load_dword v121, v[74:75], off offset:40
	global_load_dword v122, v[74:75], off offset:48
	global_load_dword v123, v[74:75], off offset:56
	v_lshl_add_u64 v[76:77], v[54:55], 0, s[14:15]
	global_load_dword v132, v[76:77], off
	v_lshl_add_u64 v[76:77], v[46:47], 0, s[14:15]
	global_load_dword v133, v[76:77], off offset:8
	global_load_dword v134, v[76:77], off offset:16
	global_load_dword v135, v[76:77], off offset:24
	global_load_dword v136, v[76:77], off offset:32
	global_load_dword v137, v[76:77], off offset:40
	global_load_dword v138, v[76:77], off offset:48
	global_load_dword v139, v[76:77], off offset:56
	s_add_u32 s14, s14, 64
	s_addc_u32 s15, s15, 0
	v_lshl_add_u64 v[72:73], v[50:51], 0, v[18:19]
	global_load_dword v108, v[72:73], off nt
	v_lshl_add_u64 v[50:51], v[50:51], 0, s[8:9]
	v_lshl_add_u64 v[72:73], v[44:45], 0, v[18:19]
	global_load_dword v109, v[72:73], off nt
	v_lshl_add_u64 v[44:45], v[44:45], 0, s[8:9]
	v_lshl_add_u64 v[72:73], v[42:43], 0, v[18:19]
	global_load_dword v110, v[72:73], off nt
	v_lshl_add_u64 v[42:43], v[42:43], 0, s[8:9]
	v_lshl_add_u64 v[72:73], v[40:41], 0, v[18:19]
	global_load_dword v111, v[72:73], off nt
	v_lshl_add_u64 v[40:41], v[40:41], 0, s[8:9]
	v_lshl_add_u64 v[72:73], v[38:39], 0, v[18:19]
	global_load_dword v112, v[72:73], off nt
	v_lshl_add_u64 v[38:39], v[38:39], 0, s[8:9]
	v_lshl_add_u64 v[72:73], v[36:37], 0, v[18:19]
	global_load_dword v113, v[72:73], off nt
	v_lshl_add_u64 v[36:37], v[36:37], 0, s[8:9]
	v_lshl_add_u64 v[72:73], v[34:35], 0, v[18:19]
	global_load_dword v114, v[72:73], off nt
	v_lshl_add_u64 v[34:35], v[34:35], 0, s[8:9]
	v_lshl_add_u64 v[72:73], v[32:33], 0, v[18:19]
	global_load_dword v115, v[72:73], off nt
	v_lshl_add_u64 v[32:33], v[32:33], 0, s[8:9]
	v_lshl_add_u64 v[74:75], v[52:53], 0, s[14:15]
	global_load_dword v124, v[74:75], off
	v_lshl_add_u64 v[74:75], v[48:49], 0, s[14:15]
	global_load_dword v125, v[74:75], off offset:8
	global_load_dword v126, v[74:75], off offset:16
	global_load_dword v127, v[74:75], off offset:24
	global_load_dword v128, v[74:75], off offset:32
	global_load_dword v129, v[74:75], off offset:40
	global_load_dword v130, v[74:75], off offset:48
	global_load_dword v131, v[74:75], off offset:56
	v_lshl_add_u64 v[76:77], v[54:55], 0, s[14:15]
	global_load_dword v140, v[76:77], off
	v_lshl_add_u64 v[76:77], v[46:47], 0, s[14:15]
	global_load_dword v141, v[76:77], off offset:8
	global_load_dword v142, v[76:77], off offset:16
	global_load_dword v143, v[76:77], off offset:24
	global_load_dword v144, v[76:77], off offset:32
	global_load_dword v145, v[76:77], off offset:40
	global_load_dword v146, v[76:77], off offset:48
	global_load_dword v147, v[76:77], off offset:56
	s_add_u32 s14, s14, 64
	s_addc_u32 s15, s15, 0
	s_waitcnt vmcnt(0)
	v_mul_f32_e32 v78, v100, v116
	ds_write_b32 v2, v78
	v_cvt_pk_bf16_f32 v79, v78, v3
	v_mul_f32_e32 v72, v100, v132
	v_lshlrev_b32_e32 v73, 16, v79
	v_pk_add_f32 v[56:57], v[56:57], v[72:73]
	v_mul_f32_e32 v78, v101, v117
	ds_write_b32 v2, v78 offset:264
	v_cvt_pk_bf16_f32 v79, v78, v3
	v_mul_f32_e32 v72, v101, v133
	v_lshlrev_b32_e32 v73, 16, v79
	v_pk_add_f32 v[56:57], v[56:57], v[72:73]
	v_mul_f32_e32 v78, v102, v118
	ds_write_b32 v2, v78 offset:528
	v_cvt_pk_bf16_f32 v79, v78, v3
	v_mul_f32_e32 v72, v102, v134
	v_lshlrev_b32_e32 v73, 16, v79
	v_pk_add_f32 v[56:57], v[56:57], v[72:73]
	v_mul_f32_e32 v78, v103, v119
	ds_write_b32 v2, v78 offset:792
	v_cvt_pk_bf16_f32 v79, v78, v3
	v_mul_f32_e32 v72, v103, v135
	v_lshlrev_b32_e32 v73, 16, v79
	v_pk_add_f32 v[56:57], v[56:57], v[72:73]
	v_mul_f32_e32 v78, v104, v120
	ds_write_b32 v2, v78 offset:1056
	v_cvt_pk_bf16_f32 v79, v78, v3
	v_mul_f32_e32 v72, v104, v136
	v_lshlrev_b32_e32 v73, 16, v79
	v_pk_add_f32 v[56:57], v[56:57], v[72:73]
	v_mul_f32_e32 v78, v105, v121
	ds_write_b32 v2, v78 offset:1320
	v_cvt_pk_bf16_f32 v79, v78, v3
	v_mul_f32_e32 v72, v105, v137
	v_lshlrev_b32_e32 v73, 16, v79
	v_pk_add_f32 v[56:57], v[56:57], v[72:73]
	v_mul_f32_e32 v78, v106, v122
	ds_write_b32 v2, v78 offset:1584
	v_cvt_pk_bf16_f32 v79, v78, v3
	v_mul_f32_e32 v72, v106, v138
	v_lshlrev_b32_e32 v73, 16, v79
	v_pk_add_f32 v[56:57], v[56:57], v[72:73]
	v_mul_f32_e32 v78, v107, v123
	ds_write_b32 v2, v78 offset:1848
	v_cvt_pk_bf16_f32 v79, v78, v3
	v_mul_f32_e32 v72, v107, v139
	v_lshlrev_b32_e32 v73, 16, v79
	v_pk_add_f32 v[56:57], v[56:57], v[72:73]
	v_add_u32_e32 v2, 0x840, v2
	v_mul_f32_e32 v78, v108, v124
	ds_write_b32 v2, v78
	v_cvt_pk_bf16_f32 v79, v78, v3
	v_mul_f32_e32 v72, v108, v140
	v_lshlrev_b32_e32 v73, 16, v79
	v_pk_add_f32 v[56:57], v[56:57], v[72:73]
	v_mul_f32_e32 v78, v109, v125
	ds_write_b32 v2, v78 offset:264
	v_cvt_pk_bf16_f32 v79, v78, v3
	v_mul_f32_e32 v72, v109, v141
	v_lshlrev_b32_e32 v73, 16, v79
	v_pk_add_f32 v[56:57], v[56:57], v[72:73]
	v_mul_f32_e32 v78, v110, v126
	ds_write_b32 v2, v78 offset:528
	v_cvt_pk_bf16_f32 v79, v78, v3
	v_mul_f32_e32 v72, v110, v142
	v_lshlrev_b32_e32 v73, 16, v79
	v_pk_add_f32 v[56:57], v[56:57], v[72:73]
	v_mul_f32_e32 v78, v111, v127
	ds_write_b32 v2, v78 offset:792
	v_cvt_pk_bf16_f32 v79, v78, v3
	v_mul_f32_e32 v72, v111, v143
	v_lshlrev_b32_e32 v73, 16, v79
	v_pk_add_f32 v[56:57], v[56:57], v[72:73]
	v_mul_f32_e32 v78, v112, v128
	ds_write_b32 v2, v78 offset:1056
	v_cvt_pk_bf16_f32 v79, v78, v3
	v_mul_f32_e32 v72, v112, v144
	v_lshlrev_b32_e32 v73, 16, v79
	v_pk_add_f32 v[56:57], v[56:57], v[72:73]
	v_mul_f32_e32 v78, v113, v129
	ds_write_b32 v2, v78 offset:1320
	v_cvt_pk_bf16_f32 v79, v78, v3
	v_mul_f32_e32 v72, v113, v145
	v_lshlrev_b32_e32 v73, 16, v79
	v_pk_add_f32 v[56:57], v[56:57], v[72:73]
	v_mul_f32_e32 v78, v114, v130
	ds_write_b32 v2, v78 offset:1584
	v_cvt_pk_bf16_f32 v79, v78, v3
	v_mul_f32_e32 v72, v114, v146
	v_lshlrev_b32_e32 v73, 16, v79
	v_pk_add_f32 v[56:57], v[56:57], v[72:73]
	v_mul_f32_e32 v78, v115, v131
	ds_write_b32 v2, v78 offset:1848
	v_cvt_pk_bf16_f32 v79, v78, v3
	v_mul_f32_e32 v72, v115, v147
	v_lshlrev_b32_e32 v73, 16, v79
	v_pk_add_f32 v[56:57], v[56:57], v[72:73]
	v_add_u32_e32 v2, 0x840, v2
	v_and_b32_e32 v32, 64, v71
	v_xor_b32_e32 v2, 32, v71
	v_add_u32_e32 v32, 64, v32
	v_cmp_lt_i32_e32 vcc, v2, v32
	s_lshl_b32 s34, s46, 5
	s_nop 0
	v_cndmask_b32_e32 v2, v71, v2, vcc
	v_lshlrev_b32_e32 v32, 2, v2
	ds_bpermute_b32 v2, v32, v57
	ds_bpermute_b32 v32, v32, v56
	s_and_saveexec_b64 s[14:15], s[4:5]
	s_cbranch_execz .LBB0_38
	s_and_b32 s0, s34, 0xff
	s_lshl_b32 s0, s0, 2
	s_waitcnt lgkmcnt(0)
	v_add_f32_e32 v34, v56, v32
	v_add_f32_e32 v2, v57, v2
	v_lshl_add_u64 v[32:33], v[8:9], 0, s[0:1]
	global_atomic_add_f32 v[32:33], v2, off
	v_lshl_add_u64 v[32:33], v[10:11], 0, s[0:1]
	global_atomic_add_f32 v[32:33], v34, off

.LBB0_42:
	v_lshl_add_u64 v[72:73], v[50:51], 0, v[18:19]
	global_load_dword v100, v[72:73], off nt
	v_lshl_add_u64 v[50:51], v[50:51], 0, s[10:11]
	v_lshl_add_u64 v[72:73], v[44:45], 0, v[18:19]
	global_load_dword v101, v[72:73], off nt
	v_lshl_add_u64 v[44:45], v[44:45], 0, s[10:11]
	v_lshl_add_u64 v[72:73], v[42:43], 0, v[18:19]
	global_load_dword v102, v[72:73], off nt
	v_lshl_add_u64 v[42:43], v[42:43], 0, s[10:11]
	v_lshl_add_u64 v[72:73], v[40:41], 0, v[18:19]
	global_load_dword v103, v[72:73], off nt
	v_lshl_add_u64 v[40:41], v[40:41], 0, s[10:11]
	v_lshl_add_u64 v[72:73], v[38:39], 0, v[18:19]
	global_load_dword v104, v[72:73], off nt
	v_lshl_add_u64 v[38:39], v[38:39], 0, s[10:11]
	v_lshl_add_u64 v[72:73], v[36:37], 0, v[18:19]
	global_load_dword v105, v[72:73], off nt
	v_lshl_add_u64 v[36:37], v[36:37], 0, s[10:11]
	v_lshl_add_u64 v[72:73], v[34:35], 0, v[18:19]
	global_load_dword v106, v[72:73], off nt
	v_lshl_add_u64 v[34:35], v[34:35], 0, s[10:11]
	v_lshl_add_u64 v[72:73], v[32:33], 0, v[18:19]
	global_load_dword v107, v[72:73], off nt
	v_lshl_add_u64 v[32:33], v[32:33], 0, s[10:11]
	v_lshl_add_u64 v[74:75], v[52:53], 0, s[14:15]
	global_load_dword v116, v[74:75], off
	v_lshl_add_u64 v[74:75], v[48:49], 0, s[14:15]
	global_load_dword v117, v[74:75], off offset:8
	global_load_dword v118, v[74:75], off offset:16
	global_load_dword v119, v[74:75], off offset:24
	global_load_dword v120, v[74:75], off offset:32
	global_load_dword v121, v[74:75], off offset:40
	global_load_dword v122, v[74:75], off offset:48
	global_load_dword v123, v[74:75], off offset:56
	v_lshl_add_u64 v[76:77], v[54:55], 0, s[14:15]
	global_load_dword v132, v[76:77], off
	v_lshl_add_u64 v[76:77], v[46:47], 0, s[14:15]
	global_load_dword v133, v[76:77], off offset:8
	global_load_dword v134, v[76:77], off offset:16
	global_load_dword v135, v[76:77], off offset:24
	global_load_dword v136, v[76:77], off offset:32
	global_load_dword v137, v[76:77], off offset:40
	global_load_dword v138, v[76:77], off offset:48
	global_load_dword v139, v[76:77], off offset:56
	s_add_u32 s14, s14, 64
	s_addc_u32 s15, s15, 0
	v_lshl_add_u64 v[72:73], v[50:51], 0, v[18:19]
	global_load_dword v108, v[72:73], off nt
	v_lshl_add_u64 v[50:51], v[50:51], 0, s[10:11]
	v_lshl_add_u64 v[72:73], v[44:45], 0, v[18:19]
	global_load_dword v109, v[72:73], off nt
	v_lshl_add_u64 v[44:45], v[44:45], 0, s[10:11]
	v_lshl_add_u64 v[72:73], v[42:43], 0, v[18:19]
	global_load_dword v110, v[72:73], off nt
	v_lshl_add_u64 v[42:43], v[42:43], 0, s[10:11]
	v_lshl_add_u64 v[72:73], v[40:41], 0, v[18:19]
	global_load_dword v111, v[72:73], off nt
	v_lshl_add_u64 v[40:41], v[40:41], 0, s[10:11]
	v_lshl_add_u64 v[72:73], v[38:39], 0, v[18:19]
	global_load_dword v112, v[72:73], off nt
	v_lshl_add_u64 v[38:39], v[38:39], 0, s[10:11]
	v_lshl_add_u64 v[72:73], v[36:37], 0, v[18:19]
	global_load_dword v113, v[72:73], off nt
	v_lshl_add_u64 v[36:37], v[36:37], 0, s[10:11]
	v_lshl_add_u64 v[72:73], v[34:35], 0, v[18:19]
	global_load_dword v114, v[72:73], off nt
	v_lshl_add_u64 v[34:35], v[34:35], 0, s[10:11]
	v_lshl_add_u64 v[72:73], v[32:33], 0, v[18:19]
	global_load_dword v115, v[72:73], off nt
	v_lshl_add_u64 v[32:33], v[32:33], 0, s[10:11]
	v_lshl_add_u64 v[74:75], v[52:53], 0, s[14:15]
	global_load_dword v124, v[74:75], off
	v_lshl_add_u64 v[74:75], v[48:49], 0, s[14:15]
	global_load_dword v125, v[74:75], off offset:8
	global_load_dword v126, v[74:75], off offset:16
	global_load_dword v127, v[74:75], off offset:24
	global_load_dword v128, v[74:75], off offset:32
	global_load_dword v129, v[74:75], off offset:40
	global_load_dword v130, v[74:75], off offset:48
	global_load_dword v131, v[74:75], off offset:56
	v_lshl_add_u64 v[76:77], v[54:55], 0, s[14:15]
	global_load_dword v140, v[76:77], off
	v_lshl_add_u64 v[76:77], v[46:47], 0, s[14:15]
	global_load_dword v141, v[76:77], off offset:8
	global_load_dword v142, v[76:77], off offset:16
	global_load_dword v143, v[76:77], off offset:24
	global_load_dword v144, v[76:77], off offset:32
	global_load_dword v145, v[76:77], off offset:40
	global_load_dword v146, v[76:77], off offset:48
	global_load_dword v147, v[76:77], off offset:56
	s_add_u32 s14, s14, 64
	s_addc_u32 s15, s15, 0
	s_waitcnt vmcnt(0)
	v_mul_f32_e32 v78, v100, v116
	ds_write_b32 v2, v78
	v_cvt_pk_bf16_f32 v79, v78, v3
	v_mul_f32_e32 v72, v100, v132
	v_lshlrev_b32_e32 v73, 16, v79
	v_pk_add_f32 v[56:57], v[56:57], v[72:73]
	v_mul_f32_e32 v78, v101, v117
	ds_write_b32 v2, v78 offset:264
	v_cvt_pk_bf16_f32 v79, v78, v3
	v_mul_f32_e32 v72, v101, v133
	v_lshlrev_b32_e32 v73, 16, v79
	v_pk_add_f32 v[56:57], v[56:57], v[72:73]
	v_mul_f32_e32 v78, v102, v118
	ds_write_b32 v2, v78 offset:528
	v_cvt_pk_bf16_f32 v79, v78, v3
	v_mul_f32_e32 v72, v102, v134
	v_lshlrev_b32_e32 v73, 16, v79
	v_pk_add_f32 v[56:57], v[56:57], v[72:73]
	v_mul_f32_e32 v78, v103, v119
	ds_write_b32 v2, v78 offset:792
	v_cvt_pk_bf16_f32 v79, v78, v3
	v_mul_f32_e32 v72, v103, v135
	v_lshlrev_b32_e32 v73, 16, v79
	v_pk_add_f32 v[56:57], v[56:57], v[72:73]
	v_mul_f32_e32 v78, v104, v120
	ds_write_b32 v2, v78 offset:1056
	v_cvt_pk_bf16_f32 v79, v78, v3
	v_mul_f32_e32 v72, v104, v136
	v_lshlrev_b32_e32 v73, 16, v79
	v_pk_add_f32 v[56:57], v[56:57], v[72:73]
	v_mul_f32_e32 v78, v105, v121
	ds_write_b32 v2, v78 offset:1320
	v_cvt_pk_bf16_f32 v79, v78, v3
	v_mul_f32_e32 v72, v105, v137
	v_lshlrev_b32_e32 v73, 16, v79
	v_pk_add_f32 v[56:57], v[56:57], v[72:73]
	v_mul_f32_e32 v78, v106, v122
	ds_write_b32 v2, v78 offset:1584
	v_cvt_pk_bf16_f32 v79, v78, v3
	v_mul_f32_e32 v72, v106, v138
	v_lshlrev_b32_e32 v73, 16, v79
	v_pk_add_f32 v[56:57], v[56:57], v[72:73]
	v_mul_f32_e32 v78, v107, v123
	ds_write_b32 v2, v78 offset:1848
	v_cvt_pk_bf16_f32 v79, v78, v3
	v_mul_f32_e32 v72, v107, v139
	v_lshlrev_b32_e32 v73, 16, v79
	v_pk_add_f32 v[56:57], v[56:57], v[72:73]
	v_add_u32_e32 v2, 0x840, v2
	v_mul_f32_e32 v78, v108, v124
	ds_write_b32 v2, v78
	v_cvt_pk_bf16_f32 v79, v78, v3
	v_mul_f32_e32 v72, v108, v140
	v_lshlrev_b32_e32 v73, 16, v79
	v_pk_add_f32 v[56:57], v[56:57], v[72:73]
	v_mul_f32_e32 v78, v109, v125
	ds_write_b32 v2, v78 offset:264
	v_cvt_pk_bf16_f32 v79, v78, v3
	v_mul_f32_e32 v72, v109, v141
	v_lshlrev_b32_e32 v73, 16, v79
	v_pk_add_f32 v[56:57], v[56:57], v[72:73]
	v_mul_f32_e32 v78, v110, v126
	ds_write_b32 v2, v78 offset:528
	v_cvt_pk_bf16_f32 v79, v78, v3
	v_mul_f32_e32 v72, v110, v142
	v_lshlrev_b32_e32 v73, 16, v79
	v_pk_add_f32 v[56:57], v[56:57], v[72:73]
	v_mul_f32_e32 v78, v111, v127
	ds_write_b32 v2, v78 offset:792
	v_cvt_pk_bf16_f32 v79, v78, v3
	v_mul_f32_e32 v72, v111, v143
	v_lshlrev_b32_e32 v73, 16, v79
	v_pk_add_f32 v[56:57], v[56:57], v[72:73]
	v_mul_f32_e32 v78, v112, v128
	ds_write_b32 v2, v78 offset:1056
	v_cvt_pk_bf16_f32 v79, v78, v3
	v_mul_f32_e32 v72, v112, v144
	v_lshlrev_b32_e32 v73, 16, v79
	v_pk_add_f32 v[56:57], v[56:57], v[72:73]
	v_mul_f32_e32 v78, v113, v129
	ds_write_b32 v2, v78 offset:1320
	v_cvt_pk_bf16_f32 v79, v78, v3
	v_mul_f32_e32 v72, v113, v145
	v_lshlrev_b32_e32 v73, 16, v79
	v_pk_add_f32 v[56:57], v[56:57], v[72:73]
	v_mul_f32_e32 v78, v114, v130
	ds_write_b32 v2, v78 offset:1584
	v_cvt_pk_bf16_f32 v79, v78, v3
	v_mul_f32_e32 v72, v114, v146
	v_lshlrev_b32_e32 v73, 16, v79
	v_pk_add_f32 v[56:57], v[56:57], v[72:73]
	v_mul_f32_e32 v78, v115, v131
	ds_write_b32 v2, v78 offset:1848
	v_cvt_pk_bf16_f32 v79, v78, v3
	v_mul_f32_e32 v72, v115, v147
	v_lshlrev_b32_e32 v73, 16, v79
	v_pk_add_f32 v[56:57], v[56:57], v[72:73]
	v_add_u32_e32 v2, 0x840, v2
	v_lshl_add_u64 v[72:73], v[50:51], 0, v[18:19]
	global_load_dword v100, v[72:73], off nt
	v_lshl_add_u64 v[50:51], v[50:51], 0, s[10:11]
	v_lshl_add_u64 v[72:73], v[44:45], 0, v[18:19]
	global_load_dword v101, v[72:73], off nt
	v_lshl_add_u64 v[44:45], v[44:45], 0, s[10:11]
	v_lshl_add_u64 v[72:73], v[42:43], 0, v[18:19]
	global_load_dword v102, v[72:73], off nt
	v_lshl_add_u64 v[42:43], v[42:43], 0, s[10:11]
	v_lshl_add_u64 v[72:73], v[40:41], 0, v[18:19]
	global_load_dword v103, v[72:73], off nt
	v_lshl_add_u64 v[40:41], v[40:41], 0, s[10:11]
	v_lshl_add_u64 v[72:73], v[38:39], 0, v[18:19]
	global_load_dword v104, v[72:73], off nt
	v_lshl_add_u64 v[38:39], v[38:39], 0, s[10:11]
	v_lshl_add_u64 v[72:73], v[36:37], 0, v[18:19]
	global_load_dword v105, v[72:73], off nt
	v_lshl_add_u64 v[36:37], v[36:37], 0, s[10:11]
	v_lshl_add_u64 v[72:73], v[34:35], 0, v[18:19]
	global_load_dword v106, v[72:73], off nt
	v_lshl_add_u64 v[34:35], v[34:35], 0, s[10:11]
	v_lshl_add_u64 v[72:73], v[32:33], 0, v[18:19]
	global_load_dword v107, v[72:73], off nt
	v_lshl_add_u64 v[32:33], v[32:33], 0, s[10:11]
	v_lshl_add_u64 v[74:75], v[52:53], 0, s[14:15]
	global_load_dword v116, v[74:75], off
	v_lshl_add_u64 v[74:75], v[48:49], 0, s[14:15]
	global_load_dword v117, v[74:75], off offset:8
	global_load_dword v118, v[74:75], off offset:16
	global_load_dword v119, v[74:75], off offset:24
	global_load_dword v120, v[74:75], off offset:32
	global_load_dword v121, v[74:75], off offset:40
	global_load_dword v122, v[74:75], off offset:48
	global_load_dword v123, v[74:75], off offset:56
	v_lshl_add_u64 v[76:77], v[54:55], 0, s[14:15]
	global_load_dword v132, v[76:77], off
	v_lshl_add_u64 v[76:77], v[46:47], 0, s[14:15]
	global_load_dword v133, v[76:77], off offset:8
	global_load_dword v134, v[76:77], off offset:16
	global_load_dword v135, v[76:77], off offset:24
	global_load_dword v136, v[76:77], off offset:32
	global_load_dword v137, v[76:77], off offset:40
	global_load_dword v138, v[76:77], off offset:48
	global_load_dword v139, v[76:77], off offset:56
	s_add_u32 s14, s14, 64
	s_addc_u32 s15, s15, 0
	v_lshl_add_u64 v[72:73], v[50:51], 0, v[18:19]
	global_load_dword v108, v[72:73], off nt
	v_lshl_add_u64 v[50:51], v[50:51], 0, s[10:11]
	v_lshl_add_u64 v[72:73], v[44:45], 0, v[18:19]
	global_load_dword v109, v[72:73], off nt
	v_lshl_add_u64 v[44:45], v[44:45], 0, s[10:11]
	v_lshl_add_u64 v[72:73], v[42:43], 0, v[18:19]
	global_load_dword v110, v[72:73], off nt
	v_lshl_add_u64 v[42:43], v[42:43], 0, s[10:11]
	v_lshl_add_u64 v[72:73], v[40:41], 0, v[18:19]
	global_load_dword v111, v[72:73], off nt
	v_lshl_add_u64 v[40:41], v[40:41], 0, s[10:11]
	v_lshl_add_u64 v[72:73], v[38:39], 0, v[18:19]
	global_load_dword v112, v[72:73], off nt
	v_lshl_add_u64 v[38:39], v[38:39], 0, s[10:11]
	v_lshl_add_u64 v[72:73], v[36:37], 0, v[18:19]
	global_load_dword v113, v[72:73], off nt
	v_lshl_add_u64 v[36:37], v[36:37], 0, s[10:11]
	v_lshl_add_u64 v[72:73], v[34:35], 0, v[18:19]
	global_load_dword v114, v[72:73], off nt
	v_lshl_add_u64 v[34:35], v[34:35], 0, s[10:11]
	v_lshl_add_u64 v[72:73], v[32:33], 0, v[18:19]
	global_load_dword v115, v[72:73], off nt
	v_lshl_add_u64 v[32:33], v[32:33], 0, s[10:11]
	v_lshl_add_u64 v[74:75], v[52:53], 0, s[14:15]
	global_load_dword v124, v[74:75], off
	v_lshl_add_u64 v[74:75], v[48:49], 0, s[14:15]
	global_load_dword v125, v[74:75], off offset:8
	global_load_dword v126, v[74:75], off offset:16
	global_load_dword v127, v[74:75], off offset:24
	global_load_dword v128, v[74:75], off offset:32
	global_load_dword v129, v[74:75], off offset:40
	global_load_dword v130, v[74:75], off offset:48
	global_load_dword v131, v[74:75], off offset:56
	v_lshl_add_u64 v[76:77], v[54:55], 0, s[14:15]
	global_load_dword v140, v[76:77], off
	v_lshl_add_u64 v[76:77], v[46:47], 0, s[14:15]
	global_load_dword v141, v[76:77], off offset:8
	global_load_dword v142, v[76:77], off offset:16
	global_load_dword v143, v[76:77], off offset:24
	global_load_dword v144, v[76:77], off offset:32
	global_load_dword v145, v[76:77], off offset:40
	global_load_dword v146, v[76:77], off offset:48
	global_load_dword v147, v[76:77], off offset:56
	s_add_u32 s14, s14, 64
	s_addc_u32 s15, s15, 0
	s_waitcnt vmcnt(0)
	v_mul_f32_e32 v78, v100, v116
	ds_write_b32 v2, v78
	v_cvt_pk_bf16_f32 v79, v78, v3
	v_mul_f32_e32 v72, v100, v132
	v_lshlrev_b32_e32 v73, 16, v79
	v_pk_add_f32 v[56:57], v[56:57], v[72:73]
	v_mul_f32_e32 v78, v101, v117
	ds_write_b32 v2, v78 offset:264
	v_cvt_pk_bf16_f32 v79, v78, v3
	v_mul_f32_e32 v72, v101, v133
	v_lshlrev_b32_e32 v73, 16, v79
	v_pk_add_f32 v[56:57], v[56:57], v[72:73]
	v_mul_f32_e32 v78, v102, v118
	ds_write_b32 v2, v78 offset:528
	v_cvt_pk_bf16_f32 v79, v78, v3
	v_mul_f32_e32 v72, v102, v134
	v_lshlrev_b32_e32 v73, 16, v79
	v_pk_add_f32 v[56:57], v[56:57], v[72:73]
	v_mul_f32_e32 v78, v103, v119
	ds_write_b32 v2, v78 offset:792
	v_cvt_pk_bf16_f32 v79, v78, v3
	v_mul_f32_e32 v72, v103, v135
	v_lshlrev_b32_e32 v73, 16, v79
	v_pk_add_f32 v[56:57], v[56:57], v[72:73]
	v_mul_f32_e32 v78, v104, v120
	ds_write_b32 v2, v78 offset:1056
	v_cvt_pk_bf16_f32 v79, v78, v3
	v_mul_f32_e32 v72, v104, v136
	v_lshlrev_b32_e32 v73, 16, v79
	v_pk_add_f32 v[56:57], v[56:57], v[72:73]
	v_mul_f32_e32 v78, v105, v121
	ds_write_b32 v2, v78 offset:1320
	v_cvt_pk_bf16_f32 v79, v78, v3
	v_mul_f32_e32 v72, v105, v137
	v_lshlrev_b32_e32 v73, 16, v79
	v_pk_add_f32 v[56:57], v[56:57], v[72:73]
	v_mul_f32_e32 v78, v106, v122
	ds_write_b32 v2, v78 offset:1584
	v_cvt_pk_bf16_f32 v79, v78, v3
	v_mul_f32_e32 v72, v106, v138
	v_lshlrev_b32_e32 v73, 16, v79
	v_pk_add_f32 v[56:57], v[56:57], v[72:73]
	v_mul_f32_e32 v78, v107, v123
	ds_write_b32 v2, v78 offset:1848
	v_cvt_pk_bf16_f32 v79, v78, v3
	v_mul_f32_e32 v72, v107, v139
	v_lshlrev_b32_e32 v73, 16, v79
	v_pk_add_f32 v[56:57], v[56:57], v[72:73]
	v_add_u32_e32 v2, 0x840, v2
	v_mul_f32_e32 v78, v108, v124
	ds_write_b32 v2, v78
	v_cvt_pk_bf16_f32 v79, v78, v3
	v_mul_f32_e32 v72, v108, v140
	v_lshlrev_b32_e32 v73, 16, v79
	v_pk_add_f32 v[56:57], v[56:57], v[72:73]
	v_mul_f32_e32 v78, v109, v125
	ds_write_b32 v2, v78 offset:264
	v_cvt_pk_bf16_f32 v79, v78, v3
	v_mul_f32_e32 v72, v109, v141
	v_lshlrev_b32_e32 v73, 16, v79
	v_pk_add_f32 v[56:57], v[56:57], v[72:73]
	v_mul_f32_e32 v78, v110, v126
	ds_write_b32 v2, v78 offset:528
	v_cvt_pk_bf16_f32 v79, v78, v3
	v_mul_f32_e32 v72, v110, v142
	v_lshlrev_b32_e32 v73, 16, v79
	v_pk_add_f32 v[56:57], v[56:57], v[72:73]
	v_mul_f32_e32 v78, v111, v127
	ds_write_b32 v2, v78 offset:792
	v_cvt_pk_bf16_f32 v79, v78, v3
	v_mul_f32_e32 v72, v111, v143
	v_lshlrev_b32_e32 v73, 16, v79
	v_pk_add_f32 v[56:57], v[56:57], v[72:73]
	v_mul_f32_e32 v78, v112, v128
	ds_write_b32 v2, v78 offset:1056
	v_cvt_pk_bf16_f32 v79, v78, v3
	v_mul_f32_e32 v72, v112, v144
	v_lshlrev_b32_e32 v73, 16, v79
	v_pk_add_f32 v[56:57], v[56:57], v[72:73]
	v_mul_f32_e32 v78, v113, v129
	ds_write_b32 v2, v78 offset:1320
	v_cvt_pk_bf16_f32 v79, v78, v3
	v_mul_f32_e32 v72, v113, v145
	v_lshlrev_b32_e32 v73, 16, v79
	v_pk_add_f32 v[56:57], v[56:57], v[72:73]
	v_mul_f32_e32 v78, v114, v130
	ds_write_b32 v2, v78 offset:1584
	v_cvt_pk_bf16_f32 v79, v78, v3
	v_mul_f32_e32 v72, v114, v146
	v_lshlrev_b32_e32 v73, 16, v79
	v_pk_add_f32 v[56:57], v[56:57], v[72:73]
	v_mul_f32_e32 v78, v115, v131
	ds_write_b32 v2, v78 offset:1848
	v_cvt_pk_bf16_f32 v79, v78, v3
	v_mul_f32_e32 v72, v115, v147
	v_lshlrev_b32_e32 v73, 16, v79
	v_pk_add_f32 v[56:57], v[56:57], v[72:73]
	v_add_u32_e32 v2, 0x840, v2
	v_and_b32_e32 v32, 64, v71
	v_xor_b32_e32 v2, 32, v71
	v_add_u32_e32 v32, 64, v32
	v_cmp_lt_i32_e32 vcc, v2, v32
	s_lshl_b32 s0, s46, 5
	s_and_b32 s34, s0, 0x7e0
	v_cndmask_b32_e32 v2, v71, v2, vcc
	v_lshlrev_b32_e32 v32, 2, v2
	ds_bpermute_b32 v2, v32, v57
	ds_bpermute_b32 v32, v32, v56
	s_and_saveexec_b64 s[14:15], s[4:5]
	s_cbranch_execz .LBB0_45
	s_lshl_b32 s0, s34, 2
	s_waitcnt lgkmcnt(0)
	v_add_f32_e32 v34, v56, v32
	v_add_f32_e32 v2, v57, v2
	v_lshl_add_u64 v[32:33], v[14:15], 0, s[0:1]
	global_atomic_add_f32 v[32:33], v2, off
	v_lshl_add_u64 v[32:33], v[16:17], 0, s[0:1]
	global_atomic_add_f32 v[32:33], v34, off

.LBB0_49:
	v_add_u32_e32 v35, s0, v2
	v_add_u32_e32 v38, 2, v35
	v_add_u32_e32 v40, 4, v35
	v_add_u32_e32 v42, 6, v35
	v_mad_i64_i32 v[36:37], s[48:49], v35, s44, v[32:33]
	v_add_u32_e32 v44, 8, v35
	v_add_u32_e32 v46, 10, v35
	v_add_u32_e32 v48, 12, v35
	v_add_u32_e32 v35, 14, v35
	v_mad_i64_i32 v[38:39], s[48:49], v38, s44, v[32:33]
	v_mad_i64_i32 v[40:41], s[48:49], v40, s44, v[32:33]
	v_mad_i64_i32 v[42:43], s[48:49], v42, s44, v[32:33]
	v_mad_i64_i32 v[44:45], s[48:49], v44, s44, v[32:33]
	v_mad_i64_i32 v[46:47], s[48:49], v46, s44, v[32:33]
	v_mad_i64_i32 v[48:49], s[48:49], v48, s44, v[32:33]
	v_mad_i64_i32 v[50:51], s[48:49], v35, s44, v[32:33]
	global_load_dword v100, v[36:37], off nt
	global_load_dword v101, v[38:39], off nt
	global_load_dword v102, v[40:41], off nt
	global_load_dword v103, v[42:43], off nt
	global_load_dword v104, v[44:45], off nt
	global_load_dword v105, v[46:47], off nt
	global_load_dword v106, v[48:49], off nt
	global_load_dword v107, v[50:51], off nt
	s_add_i32 s0, s0, 16
	v_add_u32_e32 v35, s0, v2
	v_add_u32_e32 v38, 2, v35
	v_add_u32_e32 v40, 4, v35
	v_add_u32_e32 v42, 6, v35
	v_mad_i64_i32 v[36:37], s[48:49], v35, s44, v[32:33]
	v_add_u32_e32 v44, 8, v35
	v_add_u32_e32 v46, 10, v35
	v_add_u32_e32 v48, 12, v35
	v_add_u32_e32 v35, 14, v35
	v_mad_i64_i32 v[38:39], s[48:49], v38, s44, v[32:33]
	v_mad_i64_i32 v[40:41], s[48:49], v40, s44, v[32:33]
	v_mad_i64_i32 v[42:43], s[48:49], v42, s44, v[32:33]
	v_mad_i64_i32 v[44:45], s[48:49], v44, s44, v[32:33]
	v_mad_i64_i32 v[46:47], s[48:49], v46, s44, v[32:33]
	v_mad_i64_i32 v[48:49], s[48:49], v48, s44, v[32:33]
	v_mad_i64_i32 v[50:51], s[48:49], v35, s44, v[32:33]
	global_load_dword v108, v[36:37], off nt
	global_load_dword v109, v[38:39], off nt
	global_load_dword v110, v[40:41], off nt
	global_load_dword v111, v[42:43], off nt
	global_load_dword v112, v[44:45], off nt
	global_load_dword v113, v[46:47], off nt
	global_load_dword v114, v[48:49], off nt
	global_load_dword v115, v[50:51], off nt
	s_add_i32 s0, s0, 16
	v_add_u32_e32 v35, s0, v2
	v_add_u32_e32 v38, 2, v35
	v_add_u32_e32 v40, 4, v35
	v_add_u32_e32 v42, 6, v35
	v_mad_i64_i32 v[36:37], s[48:49], v35, s44, v[32:33]
	v_add_u32_e32 v44, 8, v35
	v_add_u32_e32 v46, 10, v35
	v_add_u32_e32 v48, 12, v35
	v_add_u32_e32 v35, 14, v35
	v_mad_i64_i32 v[38:39], s[48:49], v38, s44, v[32:33]
	v_mad_i64_i32 v[40:41], s[48:49], v40, s44, v[32:33]
	v_mad_i64_i32 v[42:43], s[48:49], v42, s44, v[32:33]
	v_mad_i64_i32 v[44:45], s[48:49], v44, s44, v[32:33]
	v_mad_i64_i32 v[46:47], s[48:49], v46, s44, v[32:33]
	v_mad_i64_i32 v[48:49], s[48:49], v48, s44, v[32:33]
	v_mad_i64_i32 v[50:51], s[48:49], v35, s44, v[32:33]
	global_load_dword v116, v[36:37], off nt
	global_load_dword v117, v[38:39], off nt
	global_load_dword v118, v[40:41], off nt
	global_load_dword v119, v[42:43], off nt
	global_load_dword v120, v[44:45], off nt
	global_load_dword v121, v[46:47], off nt
	global_load_dword v122, v[48:49], off nt
	global_load_dword v123, v[50:51], off nt
	s_add_i32 s0, s0, 16
	v_add_u32_e32 v35, s0, v2
	v_add_u32_e32 v38, 2, v35
	v_add_u32_e32 v40, 4, v35
	v_add_u32_e32 v42, 6, v35
	v_mad_i64_i32 v[36:37], s[48:49], v35, s44, v[32:33]
	v_add_u32_e32 v44, 8, v35
	v_add_u32_e32 v46, 10, v35
	v_add_u32_e32 v48, 12, v35
	v_add_u32_e32 v35, 14, v35
	v_mad_i64_i32 v[38:39], s[48:49], v38, s44, v[32:33]
	v_mad_i64_i32 v[40:41], s[48:49], v40, s44, v[32:33]
	v_mad_i64_i32 v[42:43], s[48:49], v42, s44, v[32:33]
	v_mad_i64_i32 v[44:45], s[48:49], v44, s44, v[32:33]
	v_mad_i64_i32 v[46:47], s[48:49], v46, s44, v[32:33]
	v_mad_i64_i32 v[48:49], s[48:49], v48, s44, v[32:33]
	v_mad_i64_i32 v[50:51], s[48:49], v35, s44, v[32:33]
	global_load_dword v124, v[36:37], off nt
	global_load_dword v125, v[38:39], off nt
	global_load_dword v126, v[40:41], off nt
	global_load_dword v127, v[42:43], off nt
	global_load_dword v128, v[44:45], off nt
	global_load_dword v129, v[46:47], off nt
	global_load_dword v130, v[48:49], off nt
	global_load_dword v131, v[50:51], off nt
	s_add_i32 s0, s0, 16
	v_add_u32_e32 v43, 0x400, v34
	s_waitcnt vmcnt(30)
	ds_write2_b32 v34, v100, v101 offset1:66
	s_waitcnt vmcnt(28)
	ds_write2_b32 v34, v102, v103 offset0:132 offset1:198
	s_waitcnt vmcnt(26)
	ds_write2_b32 v43, v104, v105 offset0:8 offset1:74
	s_waitcnt vmcnt(24)
	ds_write2_b32 v43, v106, v107 offset0:140 offset1:206
	v_add_u32_e32 v34, 0x840, v34
	v_add_u32_e32 v43, 0x400, v34
	s_waitcnt vmcnt(22)
	ds_write2_b32 v34, v108, v109 offset1:66
	s_waitcnt vmcnt(20)
	ds_write2_b32 v34, v110, v111 offset0:132 offset1:198
	s_waitcnt vmcnt(18)
	ds_write2_b32 v43, v112, v113 offset0:8 offset1:74
	s_waitcnt vmcnt(16)
	ds_write2_b32 v43, v114, v115 offset0:140 offset1:206
	v_add_u32_e32 v34, 0x840, v34
	v_add_u32_e32 v43, 0x400, v34
	s_waitcnt vmcnt(14)
	ds_write2_b32 v34, v116, v117 offset1:66
	s_waitcnt vmcnt(12)
	ds_write2_b32 v34, v118, v119 offset0:132 offset1:198
	s_waitcnt vmcnt(10)
	ds_write2_b32 v43, v120, v121 offset0:8 offset1:74
	s_waitcnt vmcnt(8)
	ds_write2_b32 v43, v122, v123 offset0:140 offset1:206
	v_add_u32_e32 v34, 0x840, v34
	v_add_u32_e32 v43, 0x400, v34
	s_waitcnt vmcnt(6)
	ds_write2_b32 v34, v124, v125 offset1:66
	s_waitcnt vmcnt(4)
	ds_write2_b32 v34, v126, v127 offset0:132 offset1:198
	s_waitcnt vmcnt(2)
	ds_write2_b32 v43, v128, v129 offset0:8 offset1:74
	s_waitcnt vmcnt(0)
	ds_write2_b32 v43, v130, v131 offset0:140 offset1:206
	v_add_u32_e32 v34, 0x840, v34
	s_waitcnt lgkmcnt(0)
	v_or_b32_e32 v38, s14, v1
	ds_read2_b32 v[32:33], v58 offset1:33
	s_ashr_i32 s35, s34, 31
	v_ashrrev_i32_e32 v39, 31, v38
	s_waitcnt lgkmcnt(0)
	v_cvt_pk_bf16_f32 v32, v32, v33
	ds_read2_b32 v[34:35], v58 offset0:66 offset1:99
	v_lshl_add_u64 v[40:41], s[34:35], 1, v[22:23]
	v_lshlrev_b64 v[38:39], 11, v[38:39]
	s_waitcnt lgkmcnt(0)
	v_cvt_pk_bf16_f32 v33, v34, v35
	ds_read2_b32 v[34:35], v58 offset0:132 offset1:165
	v_lshl_add_u64 v[38:39], v[40:41], 0, v[38:39]
	s_waitcnt lgkmcnt(0)
	v_cvt_pk_bf16_f32 v34, v34, v35
	ds_read2_b32 v[36:37], v58 offset0:198 offset1:231
	s_waitcnt lgkmcnt(0)
	v_cvt_pk_bf16_f32 v35, v36, v37
	global_store_dwordx4 v[38:39], v[32:35], off
	v_or_b32_e32 v38, s14, v59
	v_ashrrev_i32_e32 v39, 31, v38
	ds_read2_b32 v[36:37], v58 offset0:8 offset1:41
	s_waitcnt lgkmcnt(0)
	v_cvt_pk_bf16_f32 v32, v36, v37
	ds_read2_b32 v[34:35], v58 offset0:74 offset1:107
	v_lshlrev_b64 v[38:39], 11, v[38:39]
	s_waitcnt lgkmcnt(0)
	v_cvt_pk_bf16_f32 v33, v34, v35
	ds_read2_b32 v[34:35], v58 offset0:140 offset1:173
	v_lshl_add_u64 v[38:39], v[40:41], 0, v[38:39]
	s_waitcnt lgkmcnt(0)
	v_cvt_pk_bf16_f32 v34, v34, v35
	ds_read2_b32 v[36:37], v58 offset0:206 offset1:239
	s_waitcnt lgkmcnt(0)
	v_cvt_pk_bf16_f32 v35, v36, v37
	global_store_dwordx4 v[38:39], v[32:35], off
	v_or_b32_e32 v38, s14, v60
	ds_read2_b32 v[36:37], v58 offset0:16 offset1:49
	s_waitcnt lgkmcnt(0)
	v_cvt_pk_bf16_f32 v32, v36, v37
	ds_read2_b32 v[34:35], v58 offset0:82 offset1:115
	v_ashrrev_i32_e32 v39, 31, v38
	s_waitcnt lgkmcnt(0)
	v_cvt_pk_bf16_f32 v33, v34, v35
	ds_read2_b32 v[34:35], v58 offset0:148 offset1:181
	v_lshlrev_b64 v[38:39], 11, v[38:39]
	s_waitcnt lgkmcnt(0)
	v_cvt_pk_bf16_f32 v34, v34, v35
	ds_read2_b32 v[36:37], v58 offset0:214 offset1:247
	s_waitcnt lgkmcnt(0)
	v_cvt_pk_bf16_f32 v35, v36, v37
	v_lshl_add_u64 v[38:39], v[40:41], 0, v[38:39]
	ds_read2_b32 v[36:37], v58 offset0:24 offset1:57
	global_store_dwordx4 v[38:39], v[32:35], off
	v_or_b32_e32 v38, s14, v61
	v_ashrrev_i32_e32 v39, 31, v38
	s_waitcnt lgkmcnt(0)
	v_cvt_pk_bf16_f32 v32, v36, v37
	ds_read2_b32 v[34:35], v58 offset0:90 offset1:123
	s_waitcnt lgkmcnt(0)
	v_cvt_pk_bf16_f32 v33, v34, v35
	ds_read2_b32 v[34:35], v58 offset0:156 offset1:189
	s_waitcnt lgkmcnt(0)
	v_cvt_pk_bf16_f32 v34, v34, v35
	ds_read2_b32 v[36:37], v58 offset0:222 offset1:255
	v_lshlrev_b64 v[38:39], 11, v[38:39]
	s_waitcnt lgkmcnt(0)
	v_cvt_pk_bf16_f32 v35, v36, v37
	v_lshl_add_u64 v[36:37], v[40:41], 0, v[38:39]
	global_store_dwordx4 v[36:37], v[32:35], off
	s_waitcnt lgkmcnt(0)
	s_branch .LBB0_20

.Lnl_noKe:
	s_cmp_eq_u32 s11, 0
	s_cbranch_scc0 .Lnl_me
	v_max_f32_e32 v206, v81, v81
	v_max_f32_e32 v207, v80, v80
	v_max_f32_e32 v206, v207, v206
	v_max3_f32 v206, v206, v82, v83
	v_max3_f32 v206, v206, v84, v85
	v_max3_f32 v206, v206, v86, v87
	v_max3_f32 v206, v206, v88, v89
	v_max3_f32 v206, v206, v90, v91
	v_max3_f32 v206, v206, v92, v93
	v_max3_f32 v206, v206, v94, v95
	v_max3_f32 v206, v206, v96, v97
	v_max3_f32 v206, v206, v98, v99
	v_max3_f32 v206, v206, v100, v101
	v_max3_f32 v206, v206, v102, v103
	v_max3_f32 v206, v206, v104, v105
	v_max3_f32 v206, v206, v106, v107
	v_max3_f32 v206, v206, v108, v109
	v_max3_f32 v206, v206, v110, v111
	v_mov_b32_e32 v207, v206
	s_nop 1
	v_permlane32_swap_b32_e32 v206, v207
	v_max_f32_e32 v207, v207, v207
	v_max_f32_e32 v206, v206, v206
	v_max_f32_e32 v206, v206, v207
	s_add_i32 s6, s10, 0x8000
	s_and_b32 s6, s6, 0x18000
	v_add_u32_e32 v0, s6, v175
	ds_read_b128 v[2:5], v0 offset:0
	ds_read_b128 v[6:9], v0 offset:8192
	v_add_u32_e32 v0, s6, v176
	ds_read_b128 v[10:13], v0 offset:0
	ds_read_b128 v[160:163], v0 offset:8192
	v_sub_f32_e32 v207, v206, v193
	v_cmp_ge_f32_e64 s[0:1], s27, v207
	v_max_f32_e32 v206, v206, v206
	v_max_f32_e32 v207, v193, v193
	v_max_f32_e32 v206, v207, v206
	s_cmp_eq_u64 s[0:1], exec
	s_cselect_b64 s[0:1], -1, 0
	v_cndmask_b32_e64 v14, v206, v193, s[0:1]
	v_mul_f32_e32 v207, 0xbe38aa3b, v14
	v_fmamk_f32 v208, v80, 0x3e38aa3b, v207
	v_exp_f32_e32 v80, v208
	v_fmamk_f32 v208, v81, 0x3e38aa3b, v207
	v_exp_f32_e32 v81, v208
	v_fmamk_f32 v208, v82, 0x3e38aa3b, v207
	s_waitcnt lgkmcnt(0)
	v_mfma_f32_32x32x16_bf16 v[112:127], v[2:5], v[144:147], 0
	v_exp_f32_e32 v82, v208
	v_fmamk_f32 v208, v83, 0x3e38aa3b, v207
	v_exp_f32_e32 v83, v208
	v_fmamk_f32 v208, v84, 0x3e38aa3b, v207
	v_exp_f32_e32 v84, v208
	v_fmamk_f32 v208, v85, 0x3e38aa3b, v207
	v_exp_f32_e32 v85, v208
	v_fmamk_f32 v208, v86, 0x3e38aa3b, v207
	v_exp_f32_e32 v86, v208
	v_fmamk_f32 v208, v87, 0x3e38aa3b, v207
	v_exp_f32_e32 v87, v208
	v_fmamk_f32 v208, v88, 0x3e38aa3b, v207
	v_exp_f32_e32 v88, v208
	v_fmamk_f32 v208, v89, 0x3e38aa3b, v207
	v_add_u32_e32 v0, s6, v177
	ds_read_b128 v[2:5], v0 offset:0
	v_mfma_f32_32x32x16_bf16 v[128:143], v[6:9], v[144:147], 0
	ds_read_b128 v[6:9], v0 offset:8192
	v_exp_f32_e32 v89, v208
	v_fmamk_f32 v208, v90, 0x3e38aa3b, v207
	v_exp_f32_e32 v90, v208
	v_fmamk_f32 v208, v91, 0x3e38aa3b, v207
	v_exp_f32_e32 v91, v208
	v_fmamk_f32 v208, v92, 0x3e38aa3b, v207
	v_exp_f32_e32 v92, v208
	v_fmamk_f32 v208, v93, 0x3e38aa3b, v207
	v_exp_f32_e32 v93, v208
	v_fmamk_f32 v208, v94, 0x3e38aa3b, v207
	v_exp_f32_e32 v94, v208
	v_fmamk_f32 v208, v95, 0x3e38aa3b, v207
	v_exp_f32_e32 v95, v208
	v_fmamk_f32 v208, v96, 0x3e38aa3b, v207
	v_exp_f32_e32 v96, v208
	v_add_u32_e32 v0, s6, v189
	v_mfma_f32_32x32x16_bf16 v[112:127], v[10:13], v[148:151], v[112:127]
	ds_read_b128 v[10:13], v0 offset:0
	ds_read_b128 v[182:185], v0 offset:8192
	v_fmamk_f32 v208, v97, 0x3e38aa3b, v207
	v_exp_f32_e32 v97, v208
	v_fmamk_f32 v208, v98, 0x3e38aa3b, v207
	v_exp_f32_e32 v98, v208
	v_fmamk_f32 v208, v99, 0x3e38aa3b, v207
	v_exp_f32_e32 v99, v208
	v_fmamk_f32 v208, v100, 0x3e38aa3b, v207
	v_exp_f32_e32 v100, v208
	v_fmamk_f32 v208, v101, 0x3e38aa3b, v207
	v_exp_f32_e32 v101, v208
	v_fmamk_f32 v208, v102, 0x3e38aa3b, v207
	v_exp_f32_e32 v102, v208
	v_fmamk_f32 v208, v103, 0x3e38aa3b, v207
	v_exp_f32_e32 v103, v208
	s_waitcnt lgkmcnt(0)
	v_mfma_f32_32x32x16_bf16 v[128:143], v[160:163], v[148:151], v[128:143]
	v_fmamk_f32 v208, v104, 0x3e38aa3b, v207
	v_exp_f32_e32 v104, v208
	v_fmamk_f32 v208, v105, 0x3e38aa3b, v207
	v_exp_f32_e32 v105, v208
	v_fmamk_f32 v208, v106, 0x3e38aa3b, v207
	v_exp_f32_e32 v106, v208
	v_fmamk_f32 v208, v107, 0x3e38aa3b, v207
	v_exp_f32_e32 v107, v208
	v_fmamk_f32 v208, v108, 0x3e38aa3b, v207
	v_exp_f32_e32 v108, v208
	v_fmamk_f32 v208, v109, 0x3e38aa3b, v207
	v_exp_f32_e32 v109, v208
	v_fmamk_f32 v208, v110, 0x3e38aa3b, v207
	v_exp_f32_e32 v110, v208
	v_fmamk_f32 v208, v111, 0x3e38aa3b, v207
	v_mfma_f32_32x32x16_bf16 v[112:127], v[2:5], v[152:155], v[112:127]
	v_exp_f32_e32 v111, v208
	v_sub_f32_e32 v206, v193, v206
	v_mul_f32_e32 v206, 0x3e38aa3b, v206
	v_exp_f32_e32 v206, v206
	v_add_f32_e32 v207, 0, v80
	v_cndmask_b32_e64 v194, v206, 1.0, s[0:1]
	v_mov_b32_e32 v193, v14
	v_add_f32_e32 v207, v81, v207
	v_add_f32_e32 v207, v82, v207
	v_add_f32_e32 v207, v83, v207
	v_add_f32_e32 v207, v84, v207
	v_add_f32_e32 v207, v85, v207
	v_add_f32_e32 v207, v86, v207
	v_add_f32_e32 v207, v87, v207
	v_mfma_f32_32x32x16_bf16 v[128:143], v[6:9], v[152:155], v[128:143]
	v_add_f32_e32 v207, v88, v207
	v_add_f32_e32 v207, v89, v207
	v_add_f32_e32 v207, v90, v207
	v_add_f32_e32 v207, v91, v207
	v_add_f32_e32 v207, v92, v207
	v_add_f32_e32 v207, v93, v207
	v_add_f32_e32 v207, v94, v207
	v_add_f32_e32 v207, v95, v207
	v_add_f32_e32 v207, v96, v207
	v_add_f32_e32 v207, v97, v207
	v_add_f32_e32 v207, v98, v207
	v_add_f32_e32 v207, v99, v207
	v_add_f32_e32 v207, v100, v207
	v_add_f32_e32 v207, v101, v207
	v_add_f32_e32 v207, v102, v207
	v_mfma_f32_32x32x16_bf16 v[112:127], v[10:13], v[156:159], v[112:127]
	v_add_f32_e32 v207, v103, v207
	v_add_f32_e32 v207, v104, v207
	v_add_f32_e32 v207, v105, v207
	v_add_f32_e32 v207, v106, v207
	v_add_f32_e32 v207, v107, v207
	v_add_f32_e32 v207, v108, v207
	v_add_f32_e32 v207, v109, v207
	v_add_f32_e32 v207, v110, v207
	v_add_f32_e32 v15, v111, v207
	v_mov_b32_e32 v195, v15
	v_cvt_pk_bf16_f32 v80, v80, v81
	v_cvt_pk_bf16_f32 v81, v82, v83
	v_cvt_pk_bf16_f32 v82, v84, v85
	v_cvt_pk_bf16_f32 v83, v86, v87
	v_mfma_f32_32x32x16_bf16 v[128:143], v[182:185], v[156:159], v[128:143]
	v_cvt_pk_bf16_f32 v84, v88, v89
	v_cvt_pk_bf16_f32 v85, v90, v91
	v_cvt_pk_bf16_f32 v86, v92, v93
	v_cvt_pk_bf16_f32 v87, v94, v95
	v_cvt_pk_bf16_f32 v88, v96, v97
	v_cvt_pk_bf16_f32 v89, v98, v99
	v_cvt_pk_bf16_f32 v90, v100, v101
	v_cvt_pk_bf16_f32 v91, v102, v103
	v_cvt_pk_bf16_f32 v92, v104, v105
	v_cvt_pk_bf16_f32 v93, v106, v107
	v_cvt_pk_bf16_f32 v94, v108, v109
	v_cvt_pk_bf16_f32 v95, v110, v111
	s_nop 1
	v_permlane32_swap_b32_e32 v15, v195
	v_permlane32_swap_b32_e32 v80, v82
	v_permlane32_swap_b32_e32 v81, v83
	v_permlane32_swap_b32_e32 v84, v86
	v_permlane32_swap_b32_e32 v85, v87
	v_permlane32_swap_b32_e32 v88, v90
	v_permlane32_swap_b32_e32 v89, v91
	v_permlane32_swap_b32_e32 v92, v94
	v_permlane32_swap_b32_e32 v93, v95
	v_add_f32_e32 v15, v15, v195
	v_fmac_f32_e32 v15, v192, v194
	v_mov_b32_e32 v192, v15
	v_mov_b32_e32 v194, 1.0
	s_branch .Lnl_qe

.Lnl_nors_e:
	s_add_i32 s0, s10, 0x18000
	s_and_b32 s0, s0, 0x18000
	v_add_u32_e32 v13, s0, v191
	ds_read_b64_tr_b16 v[128:129], v13 offset:0
	ds_read_b64_tr_b16 v[130:131], v13 offset:2048
	ds_read_b64_tr_b16 v[132:133], v13 offset:512
	ds_read_b64_tr_b16 v[134:135], v13 offset:2560
	ds_read_b64_tr_b16 v[136:137], v13 offset:1024
	ds_read_b64_tr_b16 v[138:139], v13 offset:3072
	ds_read_b64_tr_b16 v[140:141], v13 offset:1536
	ds_read_b64_tr_b16 v[142:143], v13 offset:3584
	v_max_f32_e32 v206, v81, v81
	v_max_f32_e32 v207, v80, v80
	v_max_f32_e32 v206, v207, v206
	v_max3_f32 v206, v206, v82, v83
	v_max3_f32 v206, v206, v84, v85
	v_max3_f32 v206, v206, v86, v87
	v_max3_f32 v206, v206, v88, v89
	v_max3_f32 v206, v206, v90, v91
	v_max3_f32 v206, v206, v92, v93
	v_max3_f32 v206, v206, v94, v95
	v_max3_f32 v206, v206, v96, v97
	v_max3_f32 v206, v206, v98, v99
	v_max3_f32 v206, v206, v100, v101
	v_max3_f32 v206, v206, v102, v103
	v_max3_f32 v206, v206, v104, v105
	v_max3_f32 v206, v206, v106, v107
	v_max3_f32 v206, v206, v108, v109
	v_max3_f32 v206, v206, v110, v111
	v_mov_b32_e32 v207, v206
	s_nop 1
	v_permlane32_swap_b32_e32 v206, v207
	v_max_f32_e32 v207, v207, v207
	v_max_f32_e32 v206, v206, v206
	v_max_f32_e32 v206, v206, v207
	s_waitcnt lgkmcnt(0)
	v_sub_f32_e32 v207, v206, v193
	v_cmp_ge_f32_e64 s[0:1], s27, v207
	v_max_f32_e32 v206, v206, v206
	v_max_f32_e32 v207, v193, v193
	v_mfma_f32_32x32x16_bf16 v[64:79], v[128:131], v[112:115], v[64:79]
	v_max_f32_e32 v206, v207, v206
	s_cmp_eq_u64 s[0:1], exec
	s_cselect_b64 s[0:1], -1, 0
	v_cndmask_b32_e64 v14, v206, v193, s[0:1]
	ds_read_b64_tr_b16 v[160:161], v13 offset:4096
	ds_read_b64_tr_b16 v[162:163], v13 offset:6144
	ds_read_b64_tr_b16 v[182:183], v13 offset:4608
	ds_read_b64_tr_b16 v[184:185], v13 offset:6656
	ds_read_b64_tr_b16 v[198:199], v13 offset:5120
	ds_read_b64_tr_b16 v[200:201], v13 offset:7168
	ds_read_b64_tr_b16 v[202:203], v13 offset:5632
	ds_read_b64_tr_b16 v[204:205], v13 offset:7680
	v_mul_f32_e32 v207, 0xbe38aa3b, v14
	v_fmamk_f32 v208, v80, 0x3e38aa3b, v207
	v_exp_f32_e32 v80, v208
	v_fmamk_f32 v208, v81, 0x3e38aa3b, v207
	v_mfma_f32_32x32x16_bf16 v[48:63], v[132:135], v[112:115], v[48:63]
	v_exp_f32_e32 v81, v208
	v_fmamk_f32 v208, v82, 0x3e38aa3b, v207
	v_exp_f32_e32 v82, v208
	v_fmamk_f32 v208, v83, 0x3e38aa3b, v207
	v_mfma_f32_32x32x16_bf16 v[32:47], v[136:139], v[112:115], v[32:47]
	v_exp_f32_e32 v83, v208
	v_fmamk_f32 v208, v84, 0x3e38aa3b, v207
	v_exp_f32_e32 v84, v208
	v_fmamk_f32 v208, v85, 0x3e38aa3b, v207
	v_mfma_f32_32x32x16_bf16 v[16:31], v[140:143], v[112:115], v[16:31]
	v_exp_f32_e32 v85, v208
	v_fmamk_f32 v208, v86, 0x3e38aa3b, v207
	v_exp_f32_e32 v86, v208
	v_fmamk_f32 v208, v87, 0x3e38aa3b, v207
	s_waitcnt lgkmcnt(0)
	v_exp_f32_e32 v87, v208
	v_fmamk_f32 v208, v88, 0x3e38aa3b, v207
	v_exp_f32_e32 v88, v208
	v_fmamk_f32 v208, v89, 0x3e38aa3b, v207
	v_mfma_f32_32x32x16_bf16 v[64:79], v[160:163], v[116:119], v[64:79]
	v_exp_f32_e32 v89, v208
	v_fmamk_f32 v208, v90, 0x3e38aa3b, v207
	v_exp_f32_e32 v90, v208
	v_fmamk_f32 v208, v91, 0x3e38aa3b, v207
	ds_read_b64_tr_b16 v[128:129], v13 offset:8192
	ds_read_b64_tr_b16 v[130:131], v13 offset:10240
	ds_read_b64_tr_b16 v[132:133], v13 offset:8704
	ds_read_b64_tr_b16 v[134:135], v13 offset:10752
	ds_read_b64_tr_b16 v[136:137], v13 offset:9216
	ds_read_b64_tr_b16 v[138:139], v13 offset:11264
	ds_read_b64_tr_b16 v[140:141], v13 offset:9728
	ds_read_b64_tr_b16 v[142:143], v13 offset:11776
	v_exp_f32_e32 v91, v208
	v_fmamk_f32 v208, v92, 0x3e38aa3b, v207
	v_exp_f32_e32 v92, v208
	v_fmamk_f32 v208, v93, 0x3e38aa3b, v207
	v_mfma_f32_32x32x16_bf16 v[48:63], v[182:185], v[116:119], v[48:63]
	v_exp_f32_e32 v93, v208
	v_fmamk_f32 v208, v94, 0x3e38aa3b, v207
	v_exp_f32_e32 v94, v208
	v_fmamk_f32 v208, v95, 0x3e38aa3b, v207
	v_mfma_f32_32x32x16_bf16 v[32:47], v[198:201], v[116:119], v[32:47]
	v_exp_f32_e32 v95, v208
	v_fmamk_f32 v208, v96, 0x3e38aa3b, v207
	v_exp_f32_e32 v96, v208
	v_fmamk_f32 v208, v97, 0x3e38aa3b, v207
	v_mfma_f32_32x32x16_bf16 v[16:31], v[202:205], v[116:119], v[16:31]
	v_exp_f32_e32 v97, v208
	v_fmamk_f32 v208, v98, 0x3e38aa3b, v207
	v_exp_f32_e32 v98, v208
	v_fmamk_f32 v208, v99, 0x3e38aa3b, v207
	s_waitcnt lgkmcnt(0)
	v_exp_f32_e32 v99, v208
	v_fmamk_f32 v208, v100, 0x3e38aa3b, v207
	v_exp_f32_e32 v100, v208
	v_fmamk_f32 v208, v101, 0x3e38aa3b, v207
	v_mfma_f32_32x32x16_bf16 v[64:79], v[128:131], v[120:123], v[64:79]
	v_exp_f32_e32 v101, v208
	v_fmamk_f32 v208, v102, 0x3e38aa3b, v207
	v_exp_f32_e32 v102, v208
	v_fmamk_f32 v208, v103, 0x3e38aa3b, v207
	ds_read_b64_tr_b16 v[160:161], v13 offset:12288
	ds_read_b64_tr_b16 v[162:163], v13 offset:14336
	ds_read_b64_tr_b16 v[182:183], v13 offset:12800
	ds_read_b64_tr_b16 v[184:185], v13 offset:14848
	ds_read_b64_tr_b16 v[198:199], v13 offset:13312
	ds_read_b64_tr_b16 v[200:201], v13 offset:15360
	ds_read_b64_tr_b16 v[202:203], v13 offset:13824
	ds_read_b64_tr_b16 v[204:205], v13 offset:15872
	v_exp_f32_e32 v103, v208
	v_fmamk_f32 v208, v104, 0x3e38aa3b, v207
	v_exp_f32_e32 v104, v208
	v_fmamk_f32 v208, v105, 0x3e38aa3b, v207
	v_mfma_f32_32x32x16_bf16 v[48:63], v[132:135], v[120:123], v[48:63]
	v_exp_f32_e32 v105, v208
	v_fmamk_f32 v208, v106, 0x3e38aa3b, v207
	v_exp_f32_e32 v106, v208
	v_fmamk_f32 v208, v107, 0x3e38aa3b, v207
	v_exp_f32_e32 v107, v208
	v_mfma_f32_32x32x16_bf16 v[32:47], v[136:139], v[120:123], v[32:47]
	v_fmamk_f32 v208, v108, 0x3e38aa3b, v207
	v_exp_f32_e32 v108, v208
	v_fmamk_f32 v208, v109, 0x3e38aa3b, v207
	v_exp_f32_e32 v109, v208
	v_mfma_f32_32x32x16_bf16 v[16:31], v[140:143], v[120:123], v[16:31]
	v_fmamk_f32 v208, v110, 0x3e38aa3b, v207
	v_exp_f32_e32 v110, v208
	v_fmamk_f32 v208, v111, 0x3e38aa3b, v207
	v_exp_f32_e32 v111, v208
	s_waitcnt lgkmcnt(0)
	v_sub_f32_e32 v206, v193, v206
	v_mul_f32_e32 v206, 0x3e38aa3b, v206
	v_exp_f32_e32 v206, v206
	v_add_f32_e32 v207, 0, v80
	v_mfma_f32_32x32x16_bf16 v[64:79], v[160:163], v[124:127], v[64:79]
	v_cndmask_b32_e64 v194, v206, 1.0, s[0:1]
	v_mov_b32_e32 v193, v14
	v_add_f32_e32 v207, v81, v207
	v_add_f32_e32 v207, v82, v207
	v_mfma_f32_32x32x16_bf16 v[48:63], v[182:185], v[124:127], v[48:63]
	v_add_f32_e32 v207, v83, v207
	v_add_f32_e32 v207, v84, v207
	v_add_f32_e32 v207, v85, v207
	v_add_f32_e32 v207, v86, v207
	v_mfma_f32_32x32x16_bf16 v[32:47], v[198:201], v[124:127], v[32:47]
	v_add_f32_e32 v207, v87, v207
	v_add_f32_e32 v207, v88, v207
	v_add_f32_e32 v207, v89, v207
	v_add_f32_e32 v207, v90, v207
	v_mfma_f32_32x32x16_bf16 v[16:31], v[202:205], v[124:127], v[16:31]
	v_add_f32_e32 v207, v91, v207
	v_add_f32_e32 v207, v92, v207
	v_add_f32_e32 v207, v93, v207
	v_add_f32_e32 v207, v94, v207
	s_add_i32 s6, s10, 0x8000
	s_and_b32 s6, s6, 0x18000
	v_add_u32_e32 v0, s6, v175
	ds_read_b128 v[2:5], v0 offset:0
	ds_read_b128 v[6:9], v0 offset:8192
	v_add_u32_e32 v0, s6, v176
	ds_read_b128 v[10:13], v0 offset:0
	ds_read_b128 v[160:163], v0 offset:8192
	v_add_f32_e32 v207, v95, v207
	v_add_f32_e32 v207, v96, v207
	v_add_f32_e32 v207, v97, v207
	v_add_f32_e32 v207, v98, v207
	s_waitcnt lgkmcnt(0)
	v_mfma_f32_32x32x16_bf16 v[112:127], v[2:5], v[144:147], 0
	v_add_f32_e32 v207, v99, v207
	v_add_f32_e32 v207, v100, v207
	v_add_f32_e32 v207, v101, v207
	v_add_f32_e32 v207, v102, v207
	v_add_u32_e32 v0, s6, v177
	ds_read_b128 v[2:5], v0 offset:0
	v_mfma_f32_32x32x16_bf16 v[128:143], v[6:9], v[144:147], 0
	ds_read_b128 v[6:9], v0 offset:8192
	v_add_f32_e32 v207, v103, v207
	v_add_f32_e32 v207, v104, v207
	v_add_f32_e32 v207, v105, v207
	v_add_f32_e32 v207, v106, v207
	v_add_u32_e32 v0, s6, v189
	v_mfma_f32_32x32x16_bf16 v[112:127], v[10:13], v[148:151], v[112:127]
	ds_read_b128 v[10:13], v0 offset:0
	ds_read_b128 v[182:185], v0 offset:8192
	v_add_f32_e32 v207, v107, v207
	v_add_f32_e32 v207, v108, v207
	v_add_f32_e32 v207, v109, v207
	v_add_f32_e32 v207, v110, v207
	s_waitcnt lgkmcnt(0)
	v_mfma_f32_32x32x16_bf16 v[128:143], v[160:163], v[148:151], v[128:143]
	v_add_f32_e32 v15, v111, v207
	v_mov_b32_e32 v195, v15
	v_cvt_pk_bf16_f32 v80, v80, v81
	v_cvt_pk_bf16_f32 v81, v82, v83
	v_mfma_f32_32x32x16_bf16 v[112:127], v[2:5], v[152:155], v[112:127]
	v_cvt_pk_bf16_f32 v82, v84, v85
	v_cvt_pk_bf16_f32 v83, v86, v87
	v_cvt_pk_bf16_f32 v84, v88, v89
	v_cvt_pk_bf16_f32 v85, v90, v91
	v_mfma_f32_32x32x16_bf16 v[128:143], v[6:9], v[152:155], v[128:143]
	v_cvt_pk_bf16_f32 v86, v92, v93
	v_cvt_pk_bf16_f32 v87, v94, v95
	v_cvt_pk_bf16_f32 v88, v96, v97
	v_cvt_pk_bf16_f32 v89, v98, v99
	v_mfma_f32_32x32x16_bf16 v[112:127], v[10:13], v[156:159], v[112:127]
	v_cvt_pk_bf16_f32 v90, v100, v101
	v_cvt_pk_bf16_f32 v91, v102, v103
	v_cvt_pk_bf16_f32 v92, v104, v105
	v_cvt_pk_bf16_f32 v93, v106, v107
	v_mfma_f32_32x32x16_bf16 v[128:143], v[182:185], v[156:159], v[128:143]
	v_cvt_pk_bf16_f32 v94, v108, v109
	v_cvt_pk_bf16_f32 v95, v110, v111
	s_nop 1
	v_permlane32_swap_b32_e32 v15, v195
	v_permlane32_swap_b32_e32 v80, v82
	v_permlane32_swap_b32_e32 v81, v83
	v_permlane32_swap_b32_e32 v84, v86
	v_permlane32_swap_b32_e32 v85, v87
	v_permlane32_swap_b32_e32 v88, v90
	v_permlane32_swap_b32_e32 v89, v91
	v_permlane32_swap_b32_e32 v92, v94
	v_permlane32_swap_b32_e32 v93, v95
	v_add_f32_e32 v15, v15, v195
	v_fmac_f32_e32 v15, v192, v194
	v_mov_b32_e32 v192, v15
.Lnl_qe:
	s_nop 3
	s_add_i32 s96, s11, 3
	s_cmp_lt_i32 s96, s9
	s_cbranch_scc1 .Lnl_wo
	s_waitcnt vmcnt(0)
	s_branch .Lnl_bo

.Lnl_noKo:
	s_add_i32 s96, s11, 2
	s_cmp_lt_i32 s96, s9
	s_cbranch_scc1 .Lnl_mo
	s_add_i32 s96, s11, 1
	s_cmp_lt_i32 s96, s8
	s_cbranch_scc1 .Lnl_mol
	v_cmp_gt_f32_e32 vcc, 1.0, v194
	s_cbranch_vccz .Lnl_nors_po
	v_pk_mul_f32 v[78:79], v[78:79], v[194:195] op_sel_hi:[1,0]
	v_pk_mul_f32 v[76:77], v[76:77], v[194:195] op_sel_hi:[1,0]
	v_pk_mul_f32 v[74:75], v[74:75], v[194:195] op_sel_hi:[1,0]
	v_pk_mul_f32 v[72:73], v[72:73], v[194:195] op_sel_hi:[1,0]
	v_pk_mul_f32 v[70:71], v[70:71], v[194:195] op_sel_hi:[1,0]
	v_pk_mul_f32 v[68:69], v[68:69], v[194:195] op_sel_hi:[1,0]
	v_pk_mul_f32 v[66:67], v[66:67], v[194:195] op_sel_hi:[1,0]
	v_pk_mul_f32 v[64:65], v[64:65], v[194:195] op_sel_hi:[1,0]
	v_pk_mul_f32 v[62:63], v[62:63], v[194:195] op_sel_hi:[1,0]
	v_pk_mul_f32 v[60:61], v[60:61], v[194:195] op_sel_hi:[1,0]
	v_pk_mul_f32 v[58:59], v[58:59], v[194:195] op_sel_hi:[1,0]
	v_pk_mul_f32 v[56:57], v[56:57], v[194:195] op_sel_hi:[1,0]
	v_pk_mul_f32 v[54:55], v[54:55], v[194:195] op_sel_hi:[1,0]
	v_pk_mul_f32 v[52:53], v[52:53], v[194:195] op_sel_hi:[1,0]
	v_pk_mul_f32 v[50:51], v[50:51], v[194:195] op_sel_hi:[1,0]
	v_pk_mul_f32 v[48:49], v[48:49], v[194:195] op_sel_hi:[1,0]
	v_pk_mul_f32 v[46:47], v[46:47], v[194:195] op_sel_hi:[1,0]
	v_pk_mul_f32 v[44:45], v[44:45], v[194:195] op_sel_hi:[1,0]
	v_pk_mul_f32 v[42:43], v[42:43], v[194:195] op_sel_hi:[1,0]
	v_pk_mul_f32 v[40:41], v[40:41], v[194:195] op_sel_hi:[1,0]
	v_pk_mul_f32 v[38:39], v[38:39], v[194:195] op_sel_hi:[1,0]
	v_pk_mul_f32 v[36:37], v[36:37], v[194:195] op_sel_hi:[1,0]
	v_pk_mul_f32 v[34:35], v[34:35], v[194:195] op_sel_hi:[1,0]
	v_pk_mul_f32 v[32:33], v[32:33], v[194:195] op_sel_hi:[1,0]
	v_pk_mul_f32 v[30:31], v[30:31], v[194:195] op_sel_hi:[1,0]
	v_pk_mul_f32 v[28:29], v[28:29], v[194:195] op_sel_hi:[1,0]
	v_pk_mul_f32 v[26:27], v[26:27], v[194:195] op_sel_hi:[1,0]
	v_pk_mul_f32 v[24:25], v[24:25], v[194:195] op_sel_hi:[1,0]
	v_pk_mul_f32 v[22:23], v[22:23], v[194:195] op_sel_hi:[1,0]
	v_pk_mul_f32 v[20:21], v[20:21], v[194:195] op_sel_hi:[1,0]
	v_pk_mul_f32 v[18:19], v[18:19], v[194:195] op_sel_hi:[1,0]
	v_pk_mul_f32 v[16:17], v[16:17], v[194:195] op_sel_hi:[1,0]

.Lnl_nors_ol:
	s_add_i32 s0, s10, 0x0
	s_and_b32 s0, s0, 0x18000
	v_add_u32_e32 v13, s0, v191
	ds_read_b64_tr_b16 v[96:97], v13 offset:0
	ds_read_b64_tr_b16 v[98:99], v13 offset:2048
	ds_read_b64_tr_b16 v[100:101], v13 offset:512
	ds_read_b64_tr_b16 v[102:103], v13 offset:2560
	ds_read_b64_tr_b16 v[104:105], v13 offset:1024
	ds_read_b64_tr_b16 v[106:107], v13 offset:3072
	ds_read_b64_tr_b16 v[108:109], v13 offset:1536
	ds_read_b64_tr_b16 v[110:111], v13 offset:3584
	v_max_f32_e32 v206, v113, v113
	v_max_f32_e32 v207, v112, v112
	v_max_f32_e32 v206, v207, v206
	v_max3_f32 v206, v206, v114, v115
	v_max3_f32 v206, v206, v116, v117
	v_max3_f32 v206, v206, v118, v119
	v_max3_f32 v206, v206, v120, v121
	v_max3_f32 v206, v206, v122, v123
	v_max3_f32 v206, v206, v124, v125
	v_max3_f32 v206, v206, v126, v127
	v_max3_f32 v206, v206, v128, v129
	v_max3_f32 v206, v206, v130, v131
	v_max3_f32 v206, v206, v132, v133
	v_max3_f32 v206, v206, v134, v135
	v_max3_f32 v206, v206, v136, v137
	v_max3_f32 v206, v206, v138, v139
	v_max3_f32 v206, v206, v140, v141
	v_max3_f32 v206, v206, v142, v143
	v_mov_b32_e32 v207, v206
	s_nop 1
	v_permlane32_swap_b32_e32 v206, v207
	v_max_f32_e32 v207, v207, v207
	v_max_f32_e32 v206, v206, v206
	v_max_f32_e32 v206, v206, v207
	s_waitcnt lgkmcnt(0)
	v_sub_f32_e32 v207, v206, v193
	v_cmp_ge_f32_e64 s[0:1], s27, v207
	v_max_f32_e32 v206, v206, v206
	v_max_f32_e32 v207, v193, v193
	v_max_f32_e32 v206, v207, v206
	v_mfma_f32_32x32x16_bf16 v[64:79], v[96:99], v[80:83], v[64:79]
	s_cmp_eq_u64 s[0:1], exec
	s_cselect_b64 s[0:1], -1, 0
	v_cndmask_b32_e64 v14, v206, v193, s[0:1]
	v_mul_f32_e32 v207, 0xbe38aa3b, v14
	v_fmamk_f32 v208, v112, 0x3e38aa3b, v207
	v_exp_f32_e32 v112, v208
	ds_read_b64_tr_b16 v[160:161], v13 offset:4096
	ds_read_b64_tr_b16 v[162:163], v13 offset:6144
	ds_read_b64_tr_b16 v[182:183], v13 offset:4608
	ds_read_b64_tr_b16 v[184:185], v13 offset:6656
	ds_read_b64_tr_b16 v[198:199], v13 offset:5120
	ds_read_b64_tr_b16 v[200:201], v13 offset:7168
	ds_read_b64_tr_b16 v[202:203], v13 offset:5632
	ds_read_b64_tr_b16 v[204:205], v13 offset:7680
	v_fmamk_f32 v208, v113, 0x3e38aa3b, v207
	v_exp_f32_e32 v113, v208
	v_fmamk_f32 v208, v114, 0x3e38aa3b, v207
	v_exp_f32_e32 v114, v208
	v_fmamk_f32 v208, v115, 0x3e38aa3b, v207
	v_mfma_f32_32x32x16_bf16 v[48:63], v[100:103], v[80:83], v[48:63]
	v_exp_f32_e32 v115, v208
	v_fmamk_f32 v208, v116, 0x3e38aa3b, v207
	v_exp_f32_e32 v116, v208
	v_fmamk_f32 v208, v117, 0x3e38aa3b, v207
	v_exp_f32_e32 v117, v208
	v_fmamk_f32 v208, v118, 0x3e38aa3b, v207
	v_mfma_f32_32x32x16_bf16 v[32:47], v[104:107], v[80:83], v[32:47]
	v_exp_f32_e32 v118, v208
	v_fmamk_f32 v208, v119, 0x3e38aa3b, v207
	v_exp_f32_e32 v119, v208
	v_fmamk_f32 v208, v120, 0x3e38aa3b, v207
	v_exp_f32_e32 v120, v208
	v_fmamk_f32 v208, v121, 0x3e38aa3b, v207
	v_mfma_f32_32x32x16_bf16 v[16:31], v[108:111], v[80:83], v[16:31]
	v_exp_f32_e32 v121, v208
	v_fmamk_f32 v208, v122, 0x3e38aa3b, v207
	v_exp_f32_e32 v122, v208
	v_fmamk_f32 v208, v123, 0x3e38aa3b, v207
	v_exp_f32_e32 v123, v208
	s_waitcnt lgkmcnt(0)
	v_fmamk_f32 v208, v124, 0x3e38aa3b, v207
	v_exp_f32_e32 v124, v208
	v_fmamk_f32 v208, v125, 0x3e38aa3b, v207
	v_exp_f32_e32 v125, v208
	v_fmamk_f32 v208, v126, 0x3e38aa3b, v207
	v_exp_f32_e32 v126, v208
	v_mfma_f32_32x32x16_bf16 v[64:79], v[160:163], v[84:87], v[64:79]
	v_fmamk_f32 v208, v127, 0x3e38aa3b, v207
	v_exp_f32_e32 v127, v208
	v_fmamk_f32 v208, v128, 0x3e38aa3b, v207
	v_exp_f32_e32 v128, v208
	v_fmamk_f32 v208, v129, 0x3e38aa3b, v207
	v_exp_f32_e32 v129, v208
	ds_read_b64_tr_b16 v[96:97], v13 offset:8192
	ds_read_b64_tr_b16 v[98:99], v13 offset:10240
	ds_read_b64_tr_b16 v[100:101], v13 offset:8704
	ds_read_b64_tr_b16 v[102:103], v13 offset:10752
	ds_read_b64_tr_b16 v[104:105], v13 offset:9216
	ds_read_b64_tr_b16 v[106:107], v13 offset:11264
	ds_read_b64_tr_b16 v[108:109], v13 offset:9728
	ds_read_b64_tr_b16 v[110:111], v13 offset:11776
	v_fmamk_f32 v208, v130, 0x3e38aa3b, v207
	v_exp_f32_e32 v130, v208
	v_fmamk_f32 v208, v131, 0x3e38aa3b, v207
	v_exp_f32_e32 v131, v208
	v_fmamk_f32 v208, v132, 0x3e38aa3b, v207
	v_mfma_f32_32x32x16_bf16 v[48:63], v[182:185], v[84:87], v[48:63]
	v_exp_f32_e32 v132, v208
	v_fmamk_f32 v208, v133, 0x3e38aa3b, v207
	v_exp_f32_e32 v133, v208
	v_fmamk_f32 v208, v134, 0x3e38aa3b, v207
	v_exp_f32_e32 v134, v208
	v_fmamk_f32 v208, v135, 0x3e38aa3b, v207
	v_mfma_f32_32x32x16_bf16 v[32:47], v[198:201], v[84:87], v[32:47]
	v_exp_f32_e32 v135, v208
	v_fmamk_f32 v208, v136, 0x3e38aa3b, v207
	v_exp_f32_e32 v136, v208
	v_fmamk_f32 v208, v137, 0x3e38aa3b, v207
	v_exp_f32_e32 v137, v208
	v_fmamk_f32 v208, v138, 0x3e38aa3b, v207
	v_mfma_f32_32x32x16_bf16 v[16:31], v[202:205], v[84:87], v[16:31]
	v_exp_f32_e32 v138, v208
	v_fmamk_f32 v208, v139, 0x3e38aa3b, v207
	v_exp_f32_e32 v139, v208
	v_fmamk_f32 v208, v140, 0x3e38aa3b, v207
	v_exp_f32_e32 v140, v208
	s_waitcnt lgkmcnt(0)
	v_fmamk_f32 v208, v141, 0x3e38aa3b, v207
	v_exp_f32_e32 v141, v208
	v_fmamk_f32 v208, v142, 0x3e38aa3b, v207
	v_exp_f32_e32 v142, v208
	v_fmamk_f32 v208, v143, 0x3e38aa3b, v207
	v_exp_f32_e32 v143, v208
	v_mfma_f32_32x32x16_bf16 v[64:79], v[96:99], v[88:91], v[64:79]
	v_sub_f32_e32 v206, v193, v206
	v_mul_f32_e32 v206, 0x3e38aa3b, v206
	v_exp_f32_e32 v206, v206
	v_add_f32_e32 v207, 0, v112
	v_cndmask_b32_e64 v194, v206, 1.0, s[0:1]
	v_mov_b32_e32 v193, v14
	ds_read_b64_tr_b16 v[160:161], v13 offset:12288
	ds_read_b64_tr_b16 v[162:163], v13 offset:14336
	ds_read_b64_tr_b16 v[182:183], v13 offset:12800
	ds_read_b64_tr_b16 v[184:185], v13 offset:14848
	ds_read_b64_tr_b16 v[198:199], v13 offset:13312
	ds_read_b64_tr_b16 v[200:201], v13 offset:15360
	ds_read_b64_tr_b16 v[202:203], v13 offset:13824
	ds_read_b64_tr_b16 v[204:205], v13 offset:15872
	v_add_f32_e32 v207, v113, v207
	v_add_f32_e32 v207, v114, v207
	v_add_f32_e32 v207, v115, v207
	v_add_f32_e32 v207, v116, v207
	v_add_f32_e32 v207, v117, v207
	v_mfma_f32_32x32x16_bf16 v[48:63], v[100:103], v[88:91], v[48:63]
	v_add_f32_e32 v207, v118, v207
	v_add_f32_e32 v207, v119, v207
	v_add_f32_e32 v207, v120, v207
	v_add_f32_e32 v207, v121, v207
	v_add_f32_e32 v207, v122, v207
	v_add_f32_e32 v207, v123, v207
	v_mfma_f32_32x32x16_bf16 v[32:47], v[104:107], v[88:91], v[32:47]
	v_add_f32_e32 v207, v124, v207
	v_add_f32_e32 v207, v125, v207
	v_add_f32_e32 v207, v126, v207
	v_add_f32_e32 v207, v127, v207
	v_add_f32_e32 v207, v128, v207
	v_add_f32_e32 v207, v129, v207
	v_mfma_f32_32x32x16_bf16 v[16:31], v[108:111], v[88:91], v[16:31]
	v_add_f32_e32 v207, v130, v207
	v_add_f32_e32 v207, v131, v207
	v_add_f32_e32 v207, v132, v207
	v_add_f32_e32 v207, v133, v207
	v_add_f32_e32 v207, v134, v207
	s_waitcnt lgkmcnt(0)
	v_add_f32_e32 v207, v135, v207
	v_add_f32_e32 v207, v136, v207
	v_add_f32_e32 v207, v137, v207
	v_add_f32_e32 v207, v138, v207
	v_add_f32_e32 v207, v139, v207
	v_add_f32_e32 v207, v140, v207
	v_mfma_f32_32x32x16_bf16 v[64:79], v[160:163], v[92:95], v[64:79]
	v_add_f32_e32 v207, v141, v207
	v_add_f32_e32 v207, v142, v207
	v_add_f32_e32 v15, v143, v207
	v_mov_b32_e32 v195, v15
	v_cvt_pk_bf16_f32 v112, v112, v113
	v_cvt_pk_bf16_f32 v113, v114, v115
	v_mfma_f32_32x32x16_bf16 v[48:63], v[182:185], v[92:95], v[48:63]
	v_cvt_pk_bf16_f32 v114, v116, v117
	v_cvt_pk_bf16_f32 v115, v118, v119
	v_cvt_pk_bf16_f32 v116, v120, v121
	v_cvt_pk_bf16_f32 v117, v122, v123
	v_cvt_pk_bf16_f32 v118, v124, v125
	v_mfma_f32_32x32x16_bf16 v[32:47], v[198:201], v[92:95], v[32:47]
	v_cvt_pk_bf16_f32 v119, v126, v127
	v_cvt_pk_bf16_f32 v120, v128, v129
	v_cvt_pk_bf16_f32 v121, v130, v131
	v_cvt_pk_bf16_f32 v122, v132, v133
	v_cvt_pk_bf16_f32 v123, v134, v135
	v_cvt_pk_bf16_f32 v124, v136, v137
	v_mfma_f32_32x32x16_bf16 v[16:31], v[202:205], v[92:95], v[16:31]
	v_cvt_pk_bf16_f32 v125, v138, v139
	v_cvt_pk_bf16_f32 v126, v140, v141
	v_cvt_pk_bf16_f32 v127, v142, v143
	s_nop 1
	v_permlane32_swap_b32_e32 v15, v195
	v_permlane32_swap_b32_e32 v112, v114
	v_permlane32_swap_b32_e32 v113, v115
	v_permlane32_swap_b32_e32 v116, v118
	v_permlane32_swap_b32_e32 v117, v119
	v_permlane32_swap_b32_e32 v120, v122
	v_permlane32_swap_b32_e32 v121, v123
	v_permlane32_swap_b32_e32 v124, v126
	v_permlane32_swap_b32_e32 v125, v127
	v_add_f32_e32 v15, v15, v195
	v_fmac_f32_e32 v15, v192, v194
	v_mov_b32_e32 v192, v15
	s_branch .Lnl_qo

.Lnl_nors_o:
	s_add_i32 s0, s10, 0x0
	s_and_b32 s0, s0, 0x18000
	v_add_u32_e32 v13, s0, v191
	ds_read_b64_tr_b16 v[96:97], v13 offset:0
	ds_read_b64_tr_b16 v[98:99], v13 offset:2048
	ds_read_b64_tr_b16 v[100:101], v13 offset:512
	ds_read_b64_tr_b16 v[102:103], v13 offset:2560
	ds_read_b64_tr_b16 v[104:105], v13 offset:1024
	ds_read_b64_tr_b16 v[106:107], v13 offset:3072
	ds_read_b64_tr_b16 v[108:109], v13 offset:1536
	ds_read_b64_tr_b16 v[110:111], v13 offset:3584
	v_max_f32_e32 v206, v113, v113
	v_max_f32_e32 v207, v112, v112
	v_max_f32_e32 v206, v207, v206
	v_max3_f32 v206, v206, v114, v115
	v_max3_f32 v206, v206, v116, v117
	v_max3_f32 v206, v206, v118, v119
	v_max3_f32 v206, v206, v120, v121
	v_max3_f32 v206, v206, v122, v123
	v_max3_f32 v206, v206, v124, v125
	v_max3_f32 v206, v206, v126, v127
	v_max3_f32 v206, v206, v128, v129
	v_max3_f32 v206, v206, v130, v131
	v_max3_f32 v206, v206, v132, v133
	v_max3_f32 v206, v206, v134, v135
	v_max3_f32 v206, v206, v136, v137
	v_max3_f32 v206, v206, v138, v139
	v_max3_f32 v206, v206, v140, v141
	v_max3_f32 v206, v206, v142, v143
	v_mov_b32_e32 v207, v206
	s_nop 1
	v_permlane32_swap_b32_e32 v206, v207
	v_max_f32_e32 v207, v207, v207
	v_max_f32_e32 v206, v206, v206
	v_max_f32_e32 v206, v206, v207
	s_waitcnt lgkmcnt(0)
	v_sub_f32_e32 v207, v206, v193
	v_cmp_ge_f32_e64 s[0:1], s27, v207
	v_max_f32_e32 v206, v206, v206
	v_max_f32_e32 v207, v193, v193
	v_mfma_f32_32x32x16_bf16 v[64:79], v[96:99], v[80:83], v[64:79]
	v_max_f32_e32 v206, v207, v206
	s_cmp_eq_u64 s[0:1], exec
	s_cselect_b64 s[0:1], -1, 0
	v_cndmask_b32_e64 v14, v206, v193, s[0:1]
	ds_read_b64_tr_b16 v[160:161], v13 offset:4096
	ds_read_b64_tr_b16 v[162:163], v13 offset:6144
	ds_read_b64_tr_b16 v[182:183], v13 offset:4608
	ds_read_b64_tr_b16 v[184:185], v13 offset:6656
	ds_read_b64_tr_b16 v[198:199], v13 offset:5120
	ds_read_b64_tr_b16 v[200:201], v13 offset:7168
	ds_read_b64_tr_b16 v[202:203], v13 offset:5632
	ds_read_b64_tr_b16 v[204:205], v13 offset:7680
	v_mul_f32_e32 v207, 0xbe38aa3b, v14
	v_fmamk_f32 v208, v112, 0x3e38aa3b, v207
	v_exp_f32_e32 v112, v208
	v_fmamk_f32 v208, v113, 0x3e38aa3b, v207
	v_mfma_f32_32x32x16_bf16 v[48:63], v[100:103], v[80:83], v[48:63]
	v_exp_f32_e32 v113, v208
	v_fmamk_f32 v208, v114, 0x3e38aa3b, v207
	v_exp_f32_e32 v114, v208
	v_fmamk_f32 v208, v115, 0x3e38aa3b, v207
	v_mfma_f32_32x32x16_bf16 v[32:47], v[104:107], v[80:83], v[32:47]
	v_exp_f32_e32 v115, v208
	v_fmamk_f32 v208, v116, 0x3e38aa3b, v207
	v_exp_f32_e32 v116, v208
	v_fmamk_f32 v208, v117, 0x3e38aa3b, v207
	v_mfma_f32_32x32x16_bf16 v[16:31], v[108:111], v[80:83], v[16:31]
	v_exp_f32_e32 v117, v208
	v_fmamk_f32 v208, v118, 0x3e38aa3b, v207
	v_exp_f32_e32 v118, v208
	v_fmamk_f32 v208, v119, 0x3e38aa3b, v207
	s_waitcnt lgkmcnt(0)
	v_exp_f32_e32 v119, v208
	v_fmamk_f32 v208, v120, 0x3e38aa3b, v207
	v_exp_f32_e32 v120, v208
	v_fmamk_f32 v208, v121, 0x3e38aa3b, v207
	v_mfma_f32_32x32x16_bf16 v[64:79], v[160:163], v[84:87], v[64:79]
	v_exp_f32_e32 v121, v208
	v_fmamk_f32 v208, v122, 0x3e38aa3b, v207
	v_exp_f32_e32 v122, v208
	v_fmamk_f32 v208, v123, 0x3e38aa3b, v207
	ds_read_b64_tr_b16 v[96:97], v13 offset:8192
	ds_read_b64_tr_b16 v[98:99], v13 offset:10240
	ds_read_b64_tr_b16 v[100:101], v13 offset:8704
	ds_read_b64_tr_b16 v[102:103], v13 offset:10752
	ds_read_b64_tr_b16 v[104:105], v13 offset:9216
	ds_read_b64_tr_b16 v[106:107], v13 offset:11264
	ds_read_b64_tr_b16 v[108:109], v13 offset:9728
	ds_read_b64_tr_b16 v[110:111], v13 offset:11776
	v_exp_f32_e32 v123, v208
	v_fmamk_f32 v208, v124, 0x3e38aa3b, v207
	v_exp_f32_e32 v124, v208
	v_fmamk_f32 v208, v125, 0x3e38aa3b, v207
	v_mfma_f32_32x32x16_bf16 v[48:63], v[182:185], v[84:87], v[48:63]
	v_exp_f32_e32 v125, v208
	v_fmamk_f32 v208, v126, 0x3e38aa3b, v207
	v_exp_f32_e32 v126, v208
	v_fmamk_f32 v208, v127, 0x3e38aa3b, v207
	v_mfma_f32_32x32x16_bf16 v[32:47], v[198:201], v[84:87], v[32:47]
	v_exp_f32_e32 v127, v208
	v_fmamk_f32 v208, v128, 0x3e38aa3b, v207
	v_exp_f32_e32 v128, v208
	v_fmamk_f32 v208, v129, 0x3e38aa3b, v207
	v_mfma_f32_32x32x16_bf16 v[16:31], v[202:205], v[84:87], v[16:31]
	v_exp_f32_e32 v129, v208
	v_fmamk_f32 v208, v130, 0x3e38aa3b, v207
	v_exp_f32_e32 v130, v208
	v_fmamk_f32 v208, v131, 0x3e38aa3b, v207
	s_waitcnt lgkmcnt(0)
	v_exp_f32_e32 v131, v208
	v_fmamk_f32 v208, v132, 0x3e38aa3b, v207
	v_exp_f32_e32 v132, v208
	v_fmamk_f32 v208, v133, 0x3e38aa3b, v207
	v_mfma_f32_32x32x16_bf16 v[64:79], v[96:99], v[88:91], v[64:79]
	v_exp_f32_e32 v133, v208
	v_fmamk_f32 v208, v134, 0x3e38aa3b, v207
	v_exp_f32_e32 v134, v208
	v_fmamk_f32 v208, v135, 0x3e38aa3b, v207
	ds_read_b64_tr_b16 v[160:161], v13 offset:12288
	ds_read_b64_tr_b16 v[162:163], v13 offset:14336
	ds_read_b64_tr_b16 v[182:183], v13 offset:12800
	ds_read_b64_tr_b16 v[184:185], v13 offset:14848
	ds_read_b64_tr_b16 v[198:199], v13 offset:13312
	ds_read_b64_tr_b16 v[200:201], v13 offset:15360
	ds_read_b64_tr_b16 v[202:203], v13 offset:13824
	ds_read_b64_tr_b16 v[204:205], v13 offset:15872
	v_exp_f32_e32 v135, v208
	v_fmamk_f32 v208, v136, 0x3e38aa3b, v207
	v_exp_f32_e32 v136, v208
	v_fmamk_f32 v208, v137, 0x3e38aa3b, v207
	v_mfma_f32_32x32x16_bf16 v[48:63], v[100:103], v[88:91], v[48:63]
	v_exp_f32_e32 v137, v208
	v_fmamk_f32 v208, v138, 0x3e38aa3b, v207
	v_exp_f32_e32 v138, v208
	v_fmamk_f32 v208, v139, 0x3e38aa3b, v207
	v_exp_f32_e32 v139, v208
	v_mfma_f32_32x32x16_bf16 v[32:47], v[104:107], v[88:91], v[32:47]
	v_fmamk_f32 v208, v140, 0x3e38aa3b, v207
	v_exp_f32_e32 v140, v208
	v_fmamk_f32 v208, v141, 0x3e38aa3b, v207
	v_exp_f32_e32 v141, v208
	v_mfma_f32_32x32x16_bf16 v[16:31], v[108:111], v[88:91], v[16:31]
	v_fmamk_f32 v208, v142, 0x3e38aa3b, v207
	v_exp_f32_e32 v142, v208
	v_fmamk_f32 v208, v143, 0x3e38aa3b, v207
	v_exp_f32_e32 v143, v208
	s_waitcnt lgkmcnt(0)
	v_sub_f32_e32 v206, v193, v206
	v_mul_f32_e32 v206, 0x3e38aa3b, v206
	v_exp_f32_e32 v206, v206
	v_add_f32_e32 v207, 0, v112
	v_mfma_f32_32x32x16_bf16 v[64:79], v[160:163], v[92:95], v[64:79]
	v_cndmask_b32_e64 v194, v206, 1.0, s[0:1]
	v_mov_b32_e32 v193, v14
	v_add_f32_e32 v207, v113, v207
	v_add_f32_e32 v207, v114, v207
	v_mfma_f32_32x32x16_bf16 v[48:63], v[182:185], v[92:95], v[48:63]
	v_add_f32_e32 v207, v115, v207
	v_add_f32_e32 v207, v116, v207
	v_add_f32_e32 v207, v117, v207
	v_add_f32_e32 v207, v118, v207
	v_mfma_f32_32x32x16_bf16 v[32:47], v[198:201], v[92:95], v[32:47]
	v_add_f32_e32 v207, v119, v207
	v_add_f32_e32 v207, v120, v207
	v_add_f32_e32 v207, v121, v207
	v_add_f32_e32 v207, v122, v207
	v_mfma_f32_32x32x16_bf16 v[16:31], v[202:205], v[92:95], v[16:31]
	v_add_f32_e32 v207, v123, v207
	v_add_f32_e32 v207, v124, v207
	v_add_f32_e32 v207, v125, v207
	v_add_f32_e32 v207, v126, v207
	s_add_i32 s6, s10, 0x10000
	s_and_b32 s6, s6, 0x18000
	v_add_u32_e32 v0, s6, v175
	ds_read_b128 v[2:5], v0 offset:0
	ds_read_b128 v[6:9], v0 offset:8192
	v_add_u32_e32 v0, s6, v176
	ds_read_b128 v[10:13], v0 offset:0
	ds_read_b128 v[160:163], v0 offset:8192
	v_add_f32_e32 v207, v127, v207
	v_add_f32_e32 v207, v128, v207
	v_add_f32_e32 v207, v129, v207
	v_add_f32_e32 v207, v130, v207
	s_waitcnt lgkmcnt(0)
	v_mfma_f32_32x32x16_bf16 v[80:95], v[2:5], v[144:147], 0
	v_add_f32_e32 v207, v131, v207
	v_add_f32_e32 v207, v132, v207
	v_add_f32_e32 v207, v133, v207
	v_add_f32_e32 v207, v134, v207
	v_add_u32_e32 v0, s6, v177
	ds_read_b128 v[2:5], v0 offset:0
	v_mfma_f32_32x32x16_bf16 v[96:111], v[6:9], v[144:147], 0
	ds_read_b128 v[6:9], v0 offset:8192
	v_add_f32_e32 v207, v135, v207
	v_add_f32_e32 v207, v136, v207
	v_add_f32_e32 v207, v137, v207
	v_add_f32_e32 v207, v138, v207
	v_add_u32_e32 v0, s6, v189
	v_mfma_f32_32x32x16_bf16 v[80:95], v[10:13], v[148:151], v[80:95]
	ds_read_b128 v[10:13], v0 offset:0
	ds_read_b128 v[182:185], v0 offset:8192
	v_add_f32_e32 v207, v139, v207
	v_add_f32_e32 v207, v140, v207
	v_add_f32_e32 v207, v141, v207
	v_add_f32_e32 v207, v142, v207
	s_waitcnt lgkmcnt(0)
	v_mfma_f32_32x32x16_bf16 v[96:111], v[160:163], v[148:151], v[96:111]
	v_add_f32_e32 v15, v143, v207
	v_mov_b32_e32 v195, v15
	v_cvt_pk_bf16_f32 v112, v112, v113
	v_cvt_pk_bf16_f32 v113, v114, v115
	v_mfma_f32_32x32x16_bf16 v[80:95], v[2:5], v[152:155], v[80:95]
	v_cvt_pk_bf16_f32 v114, v116, v117
	v_cvt_pk_bf16_f32 v115, v118, v119
	v_cvt_pk_bf16_f32 v116, v120, v121
	v_cvt_pk_bf16_f32 v117, v122, v123
	v_mfma_f32_32x32x16_bf16 v[96:111], v[6:9], v[152:155], v[96:111]
	v_cvt_pk_bf16_f32 v118, v124, v125
	v_cvt_pk_bf16_f32 v119, v126, v127
	v_cvt_pk_bf16_f32 v120, v128, v129
	v_cvt_pk_bf16_f32 v121, v130, v131
	v_mfma_f32_32x32x16_bf16 v[80:95], v[10:13], v[156:159], v[80:95]
	v_cvt_pk_bf16_f32 v122, v132, v133
	v_cvt_pk_bf16_f32 v123, v134, v135
	v_cvt_pk_bf16_f32 v124, v136, v137
	v_cvt_pk_bf16_f32 v125, v138, v139
	v_mfma_f32_32x32x16_bf16 v[96:111], v[182:185], v[156:159], v[96:111]
	v_cvt_pk_bf16_f32 v126, v140, v141
	v_cvt_pk_bf16_f32 v127, v142, v143
	s_nop 1
	v_permlane32_swap_b32_e32 v15, v195
	v_permlane32_swap_b32_e32 v112, v114
	v_permlane32_swap_b32_e32 v113, v115
	v_permlane32_swap_b32_e32 v116, v118
	v_permlane32_swap_b32_e32 v117, v119
	v_permlane32_swap_b32_e32 v120, v122
	v_permlane32_swap_b32_e32 v121, v123
	v_permlane32_swap_b32_e32 v124, v126
	v_permlane32_swap_b32_e32 v125, v127
	v_add_f32_e32 v15, v15, v195
	v_fmac_f32_e32 v15, v192, v194
	v_mov_b32_e32 v192, v15
.Lnl_qo:
	s_nop 3
	s_add_i32 s11, s11, 2
	s_add_i32 s10, s10, 0x10000
	s_add_u32 s78, s78, 0xc0000
	s_addc_u32 s79, s79, 0
	s_cmp_lt_i32 s11, s9
	s_cbranch_scc1 .LBB0_588
	s_cmp_lt_i32 s8, s9
	s_cbranch_scc1 .Lnl_done
	v_cmp_gt_f32_e32 vcc, 1.0, v194
	s_cbranch_vccz .Lnl_nors_dr
	v_pk_mul_f32 v[78:79], v[78:79], v[194:195] op_sel_hi:[1,0]
	v_pk_mul_f32 v[76:77], v[76:77], v[194:195] op_sel_hi:[1,0]
	v_pk_mul_f32 v[74:75], v[74:75], v[194:195] op_sel_hi:[1,0]
	v_pk_mul_f32 v[72:73], v[72:73], v[194:195] op_sel_hi:[1,0]
	v_pk_mul_f32 v[70:71], v[70:71], v[194:195] op_sel_hi:[1,0]
	v_pk_mul_f32 v[68:69], v[68:69], v[194:195] op_sel_hi:[1,0]
	v_pk_mul_f32 v[66:67], v[66:67], v[194:195] op_sel_hi:[1,0]
	v_pk_mul_f32 v[64:65], v[64:65], v[194:195] op_sel_hi:[1,0]
	v_pk_mul_f32 v[62:63], v[62:63], v[194:195] op_sel_hi:[1,0]
	v_pk_mul_f32 v[60:61], v[60:61], v[194:195] op_sel_hi:[1,0]
	v_pk_mul_f32 v[58:59], v[58:59], v[194:195] op_sel_hi:[1,0]
	v_pk_mul_f32 v[56:57], v[56:57], v[194:195] op_sel_hi:[1,0]
	v_pk_mul_f32 v[54:55], v[54:55], v[194:195] op_sel_hi:[1,0]
	v_pk_mul_f32 v[52:53], v[52:53], v[194:195] op_sel_hi:[1,0]
	v_pk_mul_f32 v[50:51], v[50:51], v[194:195] op_sel_hi:[1,0]
	v_pk_mul_f32 v[48:49], v[48:49], v[194:195] op_sel_hi:[1,0]
	v_pk_mul_f32 v[46:47], v[46:47], v[194:195] op_sel_hi:[1,0]
	v_pk_mul_f32 v[44:45], v[44:45], v[194:195] op_sel_hi:[1,0]
	v_pk_mul_f32 v[42:43], v[42:43], v[194:195] op_sel_hi:[1,0]
	v_pk_mul_f32 v[40:41], v[40:41], v[194:195] op_sel_hi:[1,0]
	v_pk_mul_f32 v[38:39], v[38:39], v[194:195] op_sel_hi:[1,0]
	v_pk_mul_f32 v[36:37], v[36:37], v[194:195] op_sel_hi:[1,0]
	v_pk_mul_f32 v[34:35], v[34:35], v[194:195] op_sel_hi:[1,0]
	v_pk_mul_f32 v[32:33], v[32:33], v[194:195] op_sel_hi:[1,0]
	v_pk_mul_f32 v[30:31], v[30:31], v[194:195] op_sel_hi:[1,0]
	v_pk_mul_f32 v[28:29], v[28:29], v[194:195] op_sel_hi:[1,0]
	v_pk_mul_f32 v[26:27], v[26:27], v[194:195] op_sel_hi:[1,0]
	v_pk_mul_f32 v[24:25], v[24:25], v[194:195] op_sel_hi:[1,0]
	v_pk_mul_f32 v[22:23], v[22:23], v[194:195] op_sel_hi:[1,0]
	v_pk_mul_f32 v[20:21], v[20:21], v[194:195] op_sel_hi:[1,0]
	v_pk_mul_f32 v[18:19], v[18:19], v[194:195] op_sel_hi:[1,0]
	v_pk_mul_f32 v[16:17], v[16:17], v[194:195] op_sel_hi:[1,0]

.LBB0_656:
	s_and_b64 vcc, exec, s[0:1]
	s_cbranch_vccz .LBB0_509
	v_mov_b32_e32 v220, v180
	s_add_i32 s0, s33, 0xffffff00
	s_lshr_b32 s18, s0, 4
	v_and_b32_e32 v196, 31, v220
	s_and_b32 s0, s33, 0xf0
	v_min_u32_e32 v0, 15, v196
	v_or_b32_e32 v0, s0, v0
	v_readfirstlane_b32 s15, v220
	v_or_b32_e32 v191, 0x4000, v0
	v_mov_b64_e32 v[2:3], s[76:77]
	s_bfe_u32 s19, s33, 0x20002
	s_bfe_u32 s17, s15, 0x10006
	v_mad_u64_u32 v[2:3], s[0:1], v191, s20, v[2:3]
	s_lshl_b32 s70, s19, 8
	s_lshl_b32 s0, s17, 6
	s_and_b32 s16, s33, 3
	v_lshl_add_u64 v[194:195], v[2:3], 0, s[70:71]
	s_ashr_i32 s1, s0, 31
	v_lshl_add_u64 v[2:3], s[0:1], 1, v[194:195]
	s_lshl_b32 s0, s18, 12
	s_lshl_b32 s1, s16, 10
	v_bfe_u32 v189, v220, 5, 1
	s_or_b32 s7, s0, s1
	s_mul_i32 s0, s18, 0x1040
	v_ashrrev_i32_e32 v4, 4, v220
	v_lshlrev_b32_e32 v192, 4, v189
	v_mov_b32_e32 v193, v1
	s_add_i32 s8, s0, 0x1000
	s_mov_b32 s9, s71
	v_ashrrev_i32_e32 v5, 31, v4
	v_lshl_add_u64 v[2:3], v[2:3], 0, v[192:193]
	v_lshl_add_u64 v[10:11], v[4:5], 0, s[8:9]
	v_and_b32_e32 v5, 0xfffff0, v4
	v_lshlrev_b32_e32 v14, 1, v4
	s_and_b32 s6, s15, 0x180
	s_lshl_b32 s14, s19, 7
	global_load_dwordx4 v[98:101], v[2:3], off
	global_load_dwordx4 v[102:105], v[2:3], off offset:32
	global_load_dwordx4 v[106:109], v[2:3], off offset:64
	global_load_dwordx4 v[110:113], v[2:3], off offset:96
	v_lshlrev_b32_e32 v0, 3, v220
	v_add_u32_e32 v2, s7, v4
	v_and_or_b32 v5, v14, 8, v5
	s_mov_b64 s[34:35], s[58:59]
	s_cmp_eq_u32 s6, 0
	v_ashrrev_i32_e32 v3, 31, v2
	s_mov_b32 s7, s47
	s_mov_b32 s10, s48
	v_readlane_b32 s44, v254, 4
	v_lshrrev_b32_e32 v5, 1, v5
	v_bfe_u32 v19, v0, 5, 2
	s_cselect_b64 s[0:1], -1, 0
	s_lshl_b32 s6, s19, 9
	v_and_b32_e32 v18, 0x78, v0
	v_lshlrev_b64 v[2:3], 11, v[2:3]
	v_readlane_b32 s48, v254, 8
	v_readlane_b32 s50, v254, 10
	v_readlane_b32 s51, v254, 11
	v_or_b32_e32 v0, v5, v19
	v_or_b32_e32 v6, s6, v2
	v_mov_b32_e32 v7, v3
	v_readlane_b32 s52, v254, 12
	v_readlane_b32 s53, v254, 13
	s_mov_b32 s48, s10
	s_mov_b64 s[10:11], s[50:51]
	v_lshrrev_b32_e32 v14, 1, v4
	v_lshlrev_b32_e32 v22, 9, v0
	v_and_b32_e32 v0, 3, v4
	v_readlane_b32 s47, v254, 7
	s_mov_b64 s[12:13], s[52:53]
	v_and_or_b32 v5, v14, 4, v0
	v_lshl_add_u64 v[198:199], s[10:11], 0, v[6:7]
	v_lshlrev_b32_e32 v0, 2, v18
	s_mov_b32 s47, s7
	v_lshl_add_u64 v[8:9], s[12:13], 0, v[6:7]
	v_lshl_add_u64 v[6:7], v[198:199], 0, v[0:1]
	s_mov_b32 s7, 0x10000
	s_mov_b64 s[8:9], 0x10000
	v_add_co_u32_e32 v16, vcc, s7, v6
	v_lshl_add_u64 v[8:9], v[8:9], 0, v[0:1]
	v_lshl_add_u64 v[14:15], v[6:7], 0, s[8:9]
	v_addc_co_u32_e32 v17, vcc, 0, v7, vcc
	global_load_dwordx4 v[118:121], v[6:7], off nt
	global_load_dwordx4 v[114:117], v[6:7], off offset:16 nt
	global_load_dwordx4 v[126:129], v[16:17], off nt
	global_load_dwordx4 v[122:125], v[14:15], off offset:16 nt
	global_load_dwordx4 v[134:137], v[8:9], off nt
	global_load_dwordx4 v[130:133], v[8:9], off offset:16 nt
	v_add_co_u32_e32 v14, vcc, s7, v8
	v_lshlrev_b32_e32 v0, 6, v5
	s_nop 0
	v_addc_co_u32_e32 v15, vcc, 0, v9, vcc
	global_load_dwordx4 v[146:149], v[14:15], off nt
	v_lshl_add_u64 v[14:15], v[8:9], 0, s[8:9]
	v_add_u32_e32 v5, 32, v4
	global_load_dwordx4 v[142:145], v[14:15], off offset:16 nt
	v_and_b32_e32 v14, 0xfffff0, v5
	v_lshlrev_b32_e32 v15, 1, v5
	v_and_or_b32 v14, v15, 8, v14
	v_lshrrev_b32_e32 v14, 1, v14
	v_or_b32_e32 v14, v14, v19
	v_lshlrev_b32_e32 v25, 8, v5
	v_lshl_or_b32 v5, s17, 7, v192
	v_lshlrev_b32_e32 v17, 4, v220
	v_lshlrev_b64 v[10:11], 10, v[10:11]
	v_lshlrev_b32_e32 v16, 9, v14
	v_lshlrev_b32_e32 v23, 8, v4
	v_lshl_or_b32 v4, v196, 8, v218
	v_and_b32_e32 v14, 0xf0, v17
	v_or_b32_e32 v15, 32, v5
	v_lshl_add_u64 v[12:13], s[2:3], 0, v[10:11]
	v_xad_u32 v26, v5, v14, v4
	v_xad_u32 v27, v15, v14, v4
	v_or_b32_e32 v15, 64, v5
	v_or_b32_e32 v5, 0x60, v5
	s_mov_b32 s7, 0x20000
	v_lshl_add_u64 v[12:13], v[12:13], 0, s[70:71]
	v_lshlrev_b32_e32 v20, 1, v18
	v_xad_u32 v28, v15, v14, v4
	v_xad_u32 v29, v5, v14, v4
	v_mov_b32_e32 v21, v1
	s_mov_b64 s[8:9], 0x20000
	v_add_co_u32_e32 v14, vcc, s7, v6
	v_lshl_add_u64 v[200:201], v[12:13], 0, v[20:21]
	v_lshl_add_u64 v[4:5], v[6:7], 0, s[8:9]
	v_lshl_add_u64 v[12:13], v[8:9], 0, s[8:9]
	v_addc_co_u32_e32 v15, vcc, 0, v7, vcc
	s_mov_b64 s[10:11], 0x30000
	s_mov_b32 s8, 0x30000
	global_load_dwordx4 v[138:141], v[4:5], off offset:16 nt
	v_lshl_add_u64 v[4:5], v[6:7], 0, s[10:11]
	v_add_co_u32_e32 v6, vcc, s8, v6
	v_lshl_add_u64 v[10:11], s[36:37], 0, v[10:11]
	s_nop 0
	v_addc_co_u32_e32 v7, vcc, 0, v7, vcc
	global_load_dwordx4 v[154:157], v[6:7], off nt
	global_load_dwordx4 v[158:161], v[14:15], off nt
	global_load_dwordx4 v[150:153], v[4:5], off offset:16 nt
	v_add_co_u32_e32 v4, vcc, s7, v8
	v_lshl_add_u64 v[6:7], v[8:9], 0, s[10:11]
	s_nop 0
	v_addc_co_u32_e32 v5, vcc, 0, v9, vcc
	v_add_co_u32_e32 v8, vcc, s8, v8
	global_load_dwordx4 v[162:165], v[12:13], off offset:16 nt
	s_nop 0
	v_addc_co_u32_e32 v9, vcc, 0, v9, vcc
	global_load_dwordx4 v[170:173], v[8:9], off nt
	global_load_dwordx4 v[174:177], v[4:5], off nt
	global_load_dwordx4 v[166:169], v[6:7], off offset:16 nt
	v_and_b32_e32 v219, 63, v220
	v_lshl_add_u64 v[10:11], v[10:11], 0, s[70:71]
	v_and_b32_e32 v4, 48, v20
	s_cmp_eq_u32 s16, 3
	v_and_b32_e32 v24, 0xf0, v220
	v_lshl_add_u64 v[202:203], v[10:11], 0, v[20:21]
	v_or3_b32 v21, v22, v0, v4
	v_or3_b32 v0, v16, v0, v4
	v_lshlrev_b32_e32 v4, 3, v219
	v_and_b32_e32 v5, 0xc0, v17
	v_lshlrev_b32_e32 v6, 1, v220
	s_cselect_b32 s20, 17, 16
	v_and_or_b32 v5, v4, 24, v5
	v_and_b32_e32 v6, 32, v6
	v_and_b32_e32 v4, 0x100, v4
	v_add_u32_e32 v222, 0, v0
	v_bitop3_b32 v0, v20, v23, v24 bitop3:0xde
	s_add_i32 s7, 0, 0x8000
	v_or3_b32 v22, v5, v6, v4
	v_add_u32_e32 v223, 0, v0
	v_bitop3_b32 v0, v25, v20, v24 bitop3:0xf6
	s_add_u32 s6, s12, s6
	s_waitcnt vmcnt(15)
	v_cvt_pk_bf16_f32 v4, v118, v119
	v_cvt_pk_bf16_f32 v5, v120, v121
	s_waitcnt vmcnt(14)
	v_cvt_pk_bf16_f32 v6, v114, v115
	v_cvt_pk_bf16_f32 v7, v116, v117
	s_waitcnt vmcnt(13)
	v_cvt_pk_bf16_f32 v8, v126, v127
	v_cvt_pk_bf16_f32 v9, v128, v129
	s_waitcnt vmcnt(12)
	v_cvt_pk_bf16_f32 v10, v122, v123
	v_cvt_pk_bf16_f32 v11, v124, v125
	s_waitcnt vmcnt(11)
	v_cvt_pk_bf16_f32 v12, v134, v135
	v_cvt_pk_bf16_f32 v13, v136, v137
	s_waitcnt vmcnt(10)
	v_cvt_pk_bf16_f32 v14, v130, v131
	v_cvt_pk_bf16_f32 v15, v132, v133
	s_waitcnt vmcnt(9)
	v_cvt_pk_bf16_f32 v16, v146, v147
	v_cvt_pk_bf16_f32 v17, v148, v149
	s_waitcnt vmcnt(8)
	v_cvt_pk_bf16_f32 v18, v142, v143
	v_cvt_pk_bf16_f32 v19, v144, v145
	v_add_u32_e32 v221, 0, v21
	v_add_u32_e32 v224, 0, v0
	v_add_u32_e32 v226, s7, v22
	v_add_u32_e32 v231, s7, v26
	v_add_u32_e32 v232, s7, v27
	v_add_u32_e32 v233, s7, v28
	v_add_u32_e32 v234, s7, v29
	s_addc_u32 s7, s13, 0
	v_mov_b32_e32 v34, v1
	v_mov_b32_e32 v35, v1
	v_mov_b32_e32 v48, v1
	v_mov_b32_e32 v49, v1
	v_readlane_b32 s45, v254, 5
	v_readlane_b32 s46, v254, 6
	v_readlane_b32 s54, v254, 14
	v_readlane_b32 s55, v254, 15
	v_readlane_b32 s56, v254, 16
	v_readlane_b32 s57, v254, 17
	v_readlane_b32 s58, v254, 18
	v_readlane_b32 s59, v254, 19
	ds_write_b128 v221, v[12:15]
	ds_write_b128 v222, v[16:19]
	ds_write_b128 v223, v[4:7] offset:16384
	ds_write_b128 v224, v[8:11] offset:16384
	s_mov_b64 s[8:9], 0x8000
	v_add_u32_e32 v225, 0, v22
	v_add_u32_e32 v227, 0, v26
	v_add_u32_e32 v228, 0, v27
	v_add_u32_e32 v229, 0, v28
	v_add_u32_e32 v230, 0, v29
	v_and_b32_e32 v0, 15, v220
	v_lshl_add_u64 v[208:209], s[6:7], 0, v[2:3]
	v_mov_b32_e32 v36, v1
	v_mov_b32_e32 v37, v1
	v_mov_b32_e32 v38, v1
	v_mov_b32_e32 v39, v1
	v_mov_b32_e32 v40, v1
	v_mov_b32_e32 v41, v1
	v_mov_b32_e32 v42, v1
	v_mov_b32_e32 v43, v1
	v_mov_b32_e32 v44, v1
	v_mov_b32_e32 v45, v1
	v_mov_b32_e32 v46, v1
	v_mov_b32_e32 v47, v1
	v_mov_b64_e32 v[64:65], v[48:49]
	v_mov_b64_e32 v[18:19], v[34:35]
	v_mov_b64_e32 v[2:3], v[34:35]
	s_mov_b32 s21, 0
	s_mov_b64 s[58:59], 0x50000
	s_mov_b64 s[56:57], 0xb280400
	s_mov_b64 s[54:55], 0xb280800
	s_movk_i32 s46, 0x110
	s_mov_b32 s45, 0x42b50000
	s_movk_i32 s44, 0xc0
	s_mov_b64 s[52:53], 0xb220400
	s_mov_b64 s[50:51], 0x60000
	s_mov_b32 s33, 0x20000
	v_lshl_add_u64 v[204:205], v[200:201], 0, s[8:9]
	v_lshl_add_u64 v[206:207], v[202:203], 0, s[8:9]
	v_lshlrev_b32_e32 v0, 5, v0
	v_mov_b32_e32 v235, 0
	v_mov_b32_e32 v193, 0xf149f2ca
	v_mov_b64_e32 v[62:63], v[46:47]
	v_mov_b64_e32 v[60:61], v[44:45]
	v_mov_b64_e32 v[58:59], v[42:43]
	v_mov_b64_e32 v[56:57], v[40:41]
	v_mov_b64_e32 v[54:55], v[38:39]
	v_mov_b64_e32 v[52:53], v[36:37]
	v_mov_b64_e32 v[50:51], v[34:35]
	v_mov_b64_e32 v[20:21], v[36:37]
	v_mov_b64_e32 v[22:23], v[38:39]
	v_mov_b64_e32 v[24:25], v[40:41]
	v_mov_b64_e32 v[26:27], v[42:43]
	v_mov_b64_e32 v[28:29], v[44:45]
	v_mov_b64_e32 v[30:31], v[46:47]
	v_mov_b64_e32 v[32:33], v[48:49]
	v_mov_b64_e32 v[4:5], v[36:37]
	v_mov_b64_e32 v[6:7], v[38:39]
	v_mov_b64_e32 v[8:9], v[40:41]
	v_mov_b64_e32 v[10:11], v[42:43]
	v_mov_b64_e32 v[12:13], v[44:45]
	v_mov_b64_e32 v[14:15], v[46:47]
	v_mov_b64_e32 v[16:17], v[48:49]
	v_readlane_b32 s49, v254, 9
	s_waitcnt lgkmcnt(0)
	s_barrier

.LBB0_667:
	s_add_i32 s23, s21, 1
	s_cmp_lt_u32 s23, s20
	s_cselect_b64 s[12:13], -1, 0
	s_cmp_ge_u32 s23, s20
	s_cbranch_scc1 .LBB0_671
	s_cmp_ge_u32 s22, s20
	s_cbranch_scc1 .Lsw_a0
	s_cmp_gt_u32 s21, 13
	s_cbranch_scc1 .Lsw_a4
	s_waitcnt vmcnt(8)
	s_branch .Lsw_ad
.Lsw_a0:
	s_waitcnt vmcnt(0)
	s_branch .Lsw_ad

.Lsw_ad:
	v_mov_b64_e32 v[74:75], v[174:175]
	v_mov_b64_e32 v[78:79], v[170:171]
	v_mov_b64_e32 v[70:71], v[154:155]
	v_mov_b64_e32 v[66:67], v[158:159]
	s_cmp_gt_u32 s21, 15
	v_mov_b64_e32 v[76:77], v[176:177]
	v_mov_b64_e32 v[80:81], v[172:173]
	v_mov_b64_e32 v[72:73], v[156:157]
	v_mov_b64_e32 v[68:69], v[160:161]
	s_cbranch_scc1 .LBB0_670
	v_cvt_pk_bf16_f32 v66, v158, v159
	v_cvt_pk_bf16_f32 v67, v160, v161
	v_cvt_pk_bf16_f32 v68, v138, v139
	v_cvt_pk_bf16_f32 v69, v140, v141
	v_cvt_pk_bf16_f32 v70, v154, v155
	v_cvt_pk_bf16_f32 v71, v156, v157
	v_cvt_pk_bf16_f32 v72, v150, v151
	v_cvt_pk_bf16_f32 v73, v152, v153
	v_cvt_pk_bf16_f32 v74, v174, v175
	v_cvt_pk_bf16_f32 v75, v176, v177
	v_cvt_pk_bf16_f32 v76, v162, v163
	v_cvt_pk_bf16_f32 v77, v164, v165
	v_cvt_pk_bf16_f32 v78, v170, v171
	v_cvt_pk_bf16_f32 v79, v172, v173
	v_cvt_pk_bf16_f32 v80, v166, v167
	v_cvt_pk_bf16_f32 v81, v168, v169

.LBB0_682:
	s_add_i32 s12, s21, 3
	s_cmp_ge_u32 s12, s20
	s_cbranch_scc1 .Lsw_b0
	s_cmp_gt_u32 s21, 12
	s_cbranch_scc1 .Lsw_b4
	s_waitcnt vmcnt(8)
	s_branch .Lsw_bd

.Lsw_bd:
	v_mov_b64_e32 v[66:67], v[118:119]
	v_mov_b64_e32 v[70:71], v[126:127]
	v_mov_b64_e32 v[74:75], v[134:135]
	v_mov_b64_e32 v[78:79], v[146:147]
	s_cmp_gt_u32 s21, 13
	v_mov_b64_e32 v[68:69], v[120:121]
	v_mov_b64_e32 v[72:73], v[128:129]
	v_mov_b64_e32 v[76:77], v[136:137]
	v_mov_b64_e32 v[80:81], v[148:149]
	s_cbranch_scc1 .LBB0_684
	v_cvt_pk_bf16_f32 v66, v118, v119
	v_cvt_pk_bf16_f32 v67, v120, v121
	v_cvt_pk_bf16_f32 v68, v114, v115
	v_cvt_pk_bf16_f32 v69, v116, v117
	v_cvt_pk_bf16_f32 v70, v126, v127
	v_cvt_pk_bf16_f32 v71, v128, v129
	v_cvt_pk_bf16_f32 v72, v122, v123
	v_cvt_pk_bf16_f32 v73, v124, v125
	v_cvt_pk_bf16_f32 v74, v134, v135
	v_cvt_pk_bf16_f32 v75, v136, v137
	v_cvt_pk_bf16_f32 v76, v130, v131
	v_cvt_pk_bf16_f32 v77, v132, v133
	v_cvt_pk_bf16_f32 v78, v146, v147
	v_cvt_pk_bf16_f32 v79, v148, v149
	v_cvt_pk_bf16_f32 v80, v142, v143
	v_cvt_pk_bf16_f32 v81, v144, v145
